# ACT2 (WO epilogue output, UP's A operand) also k-blocked; UP K-loop A pieces contiguous
# speedup vs baseline: 1.1161x; 1.0112x over previous
.LBB0_13:
	s_lshr_b32 s13, s12, 4
	s_and_b32 s13, s13, 24
	s_and_b32 s14, s12, 7
	s_or_b32 s13, s13, s14
	s_lshl_b32 s13, s13, 10
	v_mov_b32 v8, v198
	s_or_b32 s14, s13, s65
	v_ashrrev_i32_e32 v12, 2, v8
	v_add_u32_e32 v0, s14, v12
	v_ashrrev_i32_e32 v1, 31, v0
	v_readlane_b32 s16, v253, 21
	s_lshl_b32 s15, s12, 5
	v_lshlrev_b64 v[0:1], 6, v[0:1]
	v_readlane_b32 s17, v253, 22
	v_lshlrev_b32_e32 v2, 4, v8
	s_and_b32 s13, s15, 0xf00
	v_lshl_add_u64 v[0:1], s[16:17], 0, v[0:1]
	v_and_b32_e32 v152, 48, v2
	v_lshl_add_u64 v[14:15], v[0:1], 0, v[152:153]
	v_add_u32_e32 v0, s13, v12
	v_ashrrev_i32_e32 v1, 31, v0
	v_lshlrev_b64 v[0:1], 6, v[0:1]
	v_lshl_add_u64 v[0:1], s[4:5], 0, v[0:1]
	v_add_co_u32_e32 v54, vcc, s62, v14
	v_lshl_add_u64 v[0:1], v[0:1], 0, v[152:153]
	s_nop 0
	v_addc_co_u32_e32 v55, vcc, 0, v15, vcc
	s_lshl_b32 s16, s11, 11
	s_lshl_b32 s17, s12, 6
	s_and_b32 s18, s10, 7
	v_add_co_u32_e32 v2, vcc, s62, v0
	s_and_b32 s16, s16, 0x780000
	s_and_b32 s19, s17, 0x6000
	s_lshl_b32 s18, s18, 10
	v_lshrrev_b32_e32 v6, 2, v8
	v_addc_co_u32_e32 v3, vcc, 0, v1, vcc
	v_and_b32_e32 v6, 12, v6
	v_ashrrev_i32_e32 v13, 31, v12
	s_movk_i32 s17, 0x1230
	s_add_u32 s16, s7, s16
	v_add_co_u32_e32 v4, vcc, s33, v0
	v_lshrrev_b32_e64 v10, v6, s17
	v_lshlrev_b64 v[6:7], 11, v[12:13]
	s_addc_u32 s17, s8, 0
	s_or_b32 s18, s18, s19
	v_addc_co_u32_e32 v5, vcc, 0, v1, vcc
	v_and_b32_e32 v22, 3, v8
	v_xor_b32_e32 v8, v10, v8
	v_lshl_add_u64 v[156:157], s[16:17], 0, v[6:7]
	s_or_b32 s16, s18, s65
	v_add_co_u32_e32 v20, vcc, s72, v0
	v_lshlrev_b32_e32 v9, 6, v12
	v_lshlrev_b32_e32 v8, 4, v8
	v_add_u32_e32 v12, s16, v12
	v_addc_co_u32_e32 v21, vcc, 0, v1, vcc
	s_nop 0
	v_readfirstlane_b32 s26, v14
	v_readfirstlane_b32 s27, v15
	v_readfirstlane_b32 s28, v0
	v_readfirstlane_b32 s29, v1
	v_lshrrev_b32_e32 v250, 6, v198
	s_nop 0
	v_readfirstlane_b32 s24, v250
	s_lshl_b32 s24, s24, 10
	v_lshrrev_b32_e32 v250, 2, v200
	v_lshrrev_b32_e32 v251, 4, v200
	v_lshlrev_b32_e32 v251, 2, v251
	v_mov_b32_e32 v248, 0x1230
	v_lshrrev_b32_e32 v251, v251, v248
	v_xor_b32_e32 v251, v251, v200
	v_and_b32_e32 v251, 3, v251
	v_lshlrev_b32_e32 v251, 4, v251
	v_lshl_add_u32 v244, v250, 11, v251
	v_add_u32_e32 v245, 0x20000, v244
	v_add_u32_e32 v246, 0x40000, v244
	v_add_u32_e32 v247, 0x60000, v244
	v_lshl_add_u32 v156, v250, 6, v251
	v_add_u32_e32 v157, 0x1000, v156
	v_add_u32_e32 v158, 0x2000, v156
	v_add_u32_e32 v159, 0x3000, v156
	s_mov_b32 s25, 0
	s_add_u32 m0, s25, s24
	s_nop 0
	global_load_lds_dwordx4 v156, s[26:27]
	s_add_u32 m0, m0, 0x1000
	s_nop 0
	global_load_lds_dwordx4 v157, s[26:27]
	s_add_u32 m0, m0, 0x1000
	s_nop 0
	global_load_lds_dwordx4 v156, s[28:29]
	s_add_u32 m0, m0, 0x1000
	s_nop 0
	global_load_lds_dwordx4 v157, s[28:29]
	s_add_u32 m0, m0, 0x1000
	s_nop 0
	global_load_lds_dwordx4 v158, s[28:29]
	s_add_u32 m0, m0, 0x1000
	s_nop 0
	global_load_lds_dwordx4 v159, s[28:29]
	s_add_u32 s26, s26, 0x200000
	s_addc_u32 s27, s27, 0
	s_add_u32 s28, s28, 0x40000
	s_addc_u32 s29, s29, 0
	s_add_u32 s25, s25, 24576
	s_cmp_eq_u32 s25, 73728
	s_cselect_b32 s25, 0, s25
	s_add_u32 m0, s25, s24
	s_nop 0
	global_load_lds_dwordx4 v156, s[26:27]
	s_add_u32 m0, m0, 0x1000
	s_nop 0
	global_load_lds_dwordx4 v157, s[26:27]
	s_add_u32 m0, m0, 0x1000
	s_nop 0
	global_load_lds_dwordx4 v156, s[28:29]
	s_add_u32 m0, m0, 0x1000
	s_nop 0
	global_load_lds_dwordx4 v157, s[28:29]
	s_add_u32 m0, m0, 0x1000
	s_nop 0
	global_load_lds_dwordx4 v158, s[28:29]
	s_add_u32 m0, m0, 0x1000
	s_nop 0
	global_load_lds_dwordx4 v159, s[28:29]
	s_add_u32 s26, s26, 0x200000
	s_addc_u32 s27, s27, 0
	s_add_u32 s28, s28, 0x40000
	s_addc_u32 s29, s29, 0
	s_add_u32 s25, s25, 24576
	s_cmp_eq_u32 s25, 73728
	s_cselect_b32 s25, 0, s25
	s_add_u32 m0, s25, s24
	s_nop 0
	global_load_lds_dwordx4 v156, s[26:27]
	s_add_u32 m0, m0, 0x1000
	s_nop 0
	global_load_lds_dwordx4 v157, s[26:27]
	s_add_u32 m0, m0, 0x1000
	s_nop 0
	global_load_lds_dwordx4 v156, s[28:29]
	s_add_u32 m0, m0, 0x1000
	s_nop 0
	global_load_lds_dwordx4 v157, s[28:29]
	s_add_u32 m0, m0, 0x1000
	s_nop 0
	global_load_lds_dwordx4 v158, s[28:29]
	s_add_u32 m0, m0, 0x1000
	s_nop 0
	global_load_lds_dwordx4 v159, s[28:29]
	s_add_u32 s26, s26, 0x200000
	s_addc_u32 s27, s27, 0
	s_add_u32 s28, s28, 0x40000
	s_addc_u32 s29, s29, 0
	s_add_u32 s25, s25, 24576
	s_cmp_eq_u32 s25, 73728
	s_cselect_b32 s25, 0, s25
	v_mov_b32_e32 v24, 0
	v_mov_b32_e32 v25, v24
	v_mov_b32_e32 v26, v24
	v_mov_b32_e32 v27, v24
	v_mov_b32_e32 v28, v24
	v_mov_b32_e32 v29, v24
	v_mov_b32_e32 v84, v24
	v_mov_b32_e32 v85, v24
	v_mov_b32_e32 v86, v24
	v_mov_b32_e32 v87, v24
	v_mov_b32_e32 v88, v24
	v_mov_b32_e32 v89, v24
	v_mov_b32_e32 v90, v24
	v_mov_b32_e32 v91, v24
	v_mov_b32_e32 v92, v24
	v_mov_b32_e32 v93, v24
	v_mov_b32_e32 v94, v24
	v_mov_b32_e32 v95, v24
	v_mov_b32_e32 v96, v24
	v_mov_b32_e32 v97, v24
	v_mov_b32_e32 v98, v24
	v_mov_b32_e32 v99, v24
	v_mov_b32_e32 v54, v24
	v_mov_b32_e32 v55, v24
	v_mov_b32_e32 v100, v24
	v_mov_b32_e32 v101, v24
	v_mov_b32_e32 v30, v24
	v_mov_b32_e32 v31, v24
	v_mov_b32_e32 v32, v24
	v_mov_b32_e32 v33, v24
	v_mov_b32_e32 v34, v24
	v_mov_b32_e32 v35, v24
	v_mov_b32_e32 v36, v24
	v_mov_b32_e32 v37, v24
	v_mov_b32_e32 v38, v24
	v_mov_b32_e32 v39, v24
	v_mov_b32_e32 v40, v24
	v_mov_b32_e32 v41, v24
	v_mov_b32_e32 v42, v24
	v_mov_b32_e32 v43, v24
	v_mov_b32_e32 v44, v24
	v_mov_b32_e32 v45, v24
	v_mov_b32_e32 v46, v24
	v_mov_b32_e32 v47, v24
	v_mov_b32_e32 v48, v24
	v_mov_b32_e32 v49, v24
	v_mov_b32_e32 v50, v24
	v_mov_b32_e32 v51, v24
	v_mov_b32_e32 v52, v24
	v_mov_b32_e32 v53, v24
	v_mov_b32_e32 v102, v24
	v_mov_b32_e32 v103, v24
	v_mov_b32_e32 v104, v24
	v_mov_b32_e32 v105, v24
	v_mov_b32_e32 v106, v24
	v_mov_b32_e32 v107, v24
	v_mov_b32_e32 v116, v24
	v_mov_b32_e32 v117, v24
	v_mov_b32_e32 v118, v24
	v_mov_b32_e32 v119, v24
	v_mov_b32_e32 v128, v24
	v_mov_b32_e32 v129, v24
	v_mov_b32_e32 v130, v24
	v_mov_b32_e32 v131, v24
	v_mov_b32_e32 v108, v24
	v_mov_b32_e32 v109, v24
	v_mov_b32_e32 v110, v24
	v_mov_b32_e32 v111, v24
	v_mov_b32_e32 v112, v24
	v_mov_b32_e32 v113, v24
	v_mov_b32_e32 v114, v24
	v_mov_b32_e32 v115, v24
	v_mov_b32_e32 v120, v24
	v_mov_b32_e32 v121, v24
	v_mov_b32_e32 v122, v24
	v_mov_b32_e32 v123, v24
	v_mov_b32_e32 v124, v24
	v_mov_b32_e32 v125, v24
	v_mov_b32_e32 v126, v24
	v_mov_b32_e32 v127, v24
	v_mov_b32_e32 v64, v24
	v_mov_b32_e32 v65, v24
	v_mov_b32_e32 v66, v24
	v_mov_b32_e32 v67, v24
	v_mov_b32_e32 v68, v24
	v_mov_b32_e32 v69, v24
	v_mov_b32_e32 v70, v24
	v_mov_b32_e32 v71, v24
	v_mov_b32_e32 v80, v24
	v_mov_b32_e32 v81, v24
	v_mov_b32_e32 v82, v24
	v_mov_b32_e32 v83, v24
	v_mov_b32_e32 v56, v24
	v_mov_b32_e32 v57, v24
	v_mov_b32_e32 v58, v24
	v_mov_b32_e32 v59, v24
	v_mov_b32_e32 v132, v24
	v_mov_b32_e32 v133, v24
	v_mov_b32_e32 v134, v24
	v_mov_b32_e32 v135, v24
	v_mov_b32_e32 v136, v24
	v_mov_b32_e32 v137, v24
	v_mov_b32_e32 v138, v24
	v_mov_b32_e32 v139, v24
	v_mov_b32_e32 v140, v24
	v_mov_b32_e32 v141, v24
	v_mov_b32_e32 v142, v24
	v_mov_b32_e32 v143, v24
	v_mov_b32_e32 v144, v24
	v_mov_b32_e32 v145, v24
	v_mov_b32_e32 v146, v24
	v_mov_b32_e32 v147, v24
	v_mov_b32_e32 v76, v24
	v_mov_b32_e32 v77, v24
	v_mov_b32_e32 v78, v24
	v_mov_b32_e32 v79, v24
	v_mov_b32_e32 v72, v24
	v_mov_b32_e32 v73, v24
	v_mov_b32_e32 v74, v24
	v_mov_b32_e32 v75, v24
	v_mov_b32_e32 v60, v24
	v_mov_b32_e32 v61, v24
	v_mov_b32_e32 v62, v24
	v_mov_b32_e32 v63, v24
	v_mov_b32_e32 v148, v24
	v_mov_b32_e32 v149, v24
	v_mov_b32_e32 v150, v24
	v_mov_b32_e32 v151, v24
	s_waitcnt vmcnt(12)
	s_barrier
	s_mov_b32 s30, 0
	v_add_u32_e32 v248, s30, v155
	v_add_u32_e32 v249, s30, v160
	ds_read_b128 v[186:189], v248
	ds_read_b128 v[212:215], v249 offset:8192
	ds_read_b128 v[190:193], v248 offset:1024
	ds_read_b128 v[216:219], v249 offset:9216
	ds_read_b128 v[194:197], v248 offset:2048
	ds_read_b128 v[220:223], v249 offset:10240
	ds_read_b128 v[208:211], v248 offset:3072
	ds_read_b128 v[224:227], v249 offset:11264
	ds_read_b128 v[228:231], v249 offset:12288
	ds_read_b128 v[232:235], v249 offset:13312
	ds_read_b128 v[236:239], v249 offset:14336
	ds_read_b128 v[240:243], v249 offset:15360
	s_add_u32 s30, s30, 24576
	s_cmp_eq_u32 s30, 73728
	s_cselect_b32 s30, 0, s30
	s_waitcnt vmcnt(6)
	s_waitcnt lgkmcnt(0)
	s_barrier
	s_mov_b32 s31, 14
.Lgm0_loop:
	v_add_u32_e32 v248, s30, v155
	v_add_u32_e32 v249, s30, v160
	v_mfma_f32_16x16x32_bf16 v[128:131], v[212:215], v[186:189], v[128:131]
	ds_read_b128 v[0:3], v248
	v_mfma_f32_16x16x32_bf16 v[96:99], v[212:215], v[190:193], v[96:99]
	ds_read_b128 v[16:19], v249 offset:8192
	v_mfma_f32_16x16x32_bf16 v[108:111], v[212:215], v[194:197], v[108:111]
	ds_read_b128 v[4:7], v248 offset:1024
	v_mfma_f32_16x16x32_bf16 v[132:135], v[212:215], v[208:211], v[132:135]
	ds_read_b128 v[20:23], v249 offset:9216
	v_mfma_f32_16x16x32_bf16 v[116:119], v[216:219], v[186:189], v[116:119]
	ds_read_b128 v[8:11], v248 offset:2048
	v_mfma_f32_16x16x32_bf16 v[92:95], v[216:219], v[190:193], v[92:95]
	ds_read_b128 v[162:165], v249 offset:10240
	v_mfma_f32_16x16x32_bf16 v[112:115], v[216:219], v[194:197], v[112:115]
	ds_read_b128 v[12:15], v248 offset:3072
	v_mfma_f32_16x16x32_bf16 v[136:139], v[216:219], v[208:211], v[136:139]
	ds_read_b128 v[166:169], v249 offset:11264
	v_mfma_f32_16x16x32_bf16 v[104:107], v[220:223], v[186:189], v[104:107]
	ds_read_b128 v[170:173], v249 offset:12288
	v_mfma_f32_16x16x32_bf16 v[88:91], v[220:223], v[190:193], v[88:91]
	ds_read_b128 v[174:177], v249 offset:13312
	v_mfma_f32_16x16x32_bf16 v[120:123], v[220:223], v[194:197], v[120:123]
	ds_read_b128 v[178:181], v249 offset:14336
	v_mfma_f32_16x16x32_bf16 v[140:143], v[220:223], v[208:211], v[140:143]
	ds_read_b128 v[182:185], v249 offset:15360
	s_add_u32 m0, s25, s24
	v_mfma_f32_16x16x32_bf16 v[100:103], v[224:227], v[186:189], v[100:103]
	global_load_lds_dwordx4 v156, s[26:27]
	v_mfma_f32_16x16x32_bf16 v[84:87], v[224:227], v[190:193], v[84:87]
	v_mfma_f32_16x16x32_bf16 v[124:127], v[224:227], v[194:197], v[124:127]
	s_add_u32 m0, m0, 0x1000
	v_mfma_f32_16x16x32_bf16 v[144:147], v[224:227], v[208:211], v[144:147]
	global_load_lds_dwordx4 v157, s[26:27]
	v_mfma_f32_16x16x32_bf16 v[52:55], v[228:231], v[186:189], v[52:55]
	v_mfma_f32_16x16x32_bf16 v[36:39], v[228:231], v[190:193], v[36:39]
	s_add_u32 m0, m0, 0x1000
	v_mfma_f32_16x16x32_bf16 v[64:67], v[228:231], v[194:197], v[64:67]
	global_load_lds_dwordx4 v156, s[28:29]
	v_mfma_f32_16x16x32_bf16 v[76:79], v[228:231], v[208:211], v[76:79]
	v_mfma_f32_16x16x32_bf16 v[48:51], v[232:235], v[186:189], v[48:51]
	s_add_u32 m0, m0, 0x1000
	v_mfma_f32_16x16x32_bf16 v[32:35], v[232:235], v[190:193], v[32:35]
	global_load_lds_dwordx4 v157, s[28:29]
	v_mfma_f32_16x16x32_bf16 v[68:71], v[232:235], v[194:197], v[68:71]
	v_mfma_f32_16x16x32_bf16 v[72:75], v[232:235], v[208:211], v[72:75]
	s_add_u32 m0, m0, 0x1000
	v_mfma_f32_16x16x32_bf16 v[44:47], v[236:239], v[186:189], v[44:47]
	global_load_lds_dwordx4 v158, s[28:29]
	v_mfma_f32_16x16x32_bf16 v[28:31], v[236:239], v[190:193], v[28:31]
	v_mfma_f32_16x16x32_bf16 v[80:83], v[236:239], v[194:197], v[80:83]
	s_add_u32 m0, m0, 0x1000
	v_mfma_f32_16x16x32_bf16 v[60:63], v[236:239], v[208:211], v[60:63]
	global_load_lds_dwordx4 v159, s[28:29]
	v_mfma_f32_16x16x32_bf16 v[40:43], v[240:243], v[186:189], v[40:43]
	v_mfma_f32_16x16x32_bf16 v[24:27], v[240:243], v[190:193], v[24:27]
	v_mfma_f32_16x16x32_bf16 v[56:59], v[240:243], v[194:197], v[56:59]
	v_mfma_f32_16x16x32_bf16 v[148:151], v[240:243], v[208:211], v[148:151]
	s_add_u32 s26, s26, 0x200000
	s_addc_u32 s27, s27, 0
	s_add_u32 s28, s28, 0x40000
	s_addc_u32 s29, s29, 0
	s_add_u32 s25, s25, 24576
	s_cmp_eq_u32 s25, 73728
	s_cselect_b32 s25, 0, s25
	s_add_u32 s30, s30, 24576
	s_cmp_eq_u32 s30, 73728
	s_cselect_b32 s30, 0, s30
	s_waitcnt vmcnt(6)
	s_waitcnt lgkmcnt(0)
	s_barrier
	v_add_u32_e32 v248, s30, v155
	v_add_u32_e32 v249, s30, v160
	v_mfma_f32_16x16x32_bf16 v[128:131], v[16:19], v[0:3], v[128:131]
	ds_read_b128 v[186:189], v248
	v_mfma_f32_16x16x32_bf16 v[96:99], v[16:19], v[4:7], v[96:99]
	ds_read_b128 v[212:215], v249 offset:8192
	v_mfma_f32_16x16x32_bf16 v[108:111], v[16:19], v[8:11], v[108:111]
	ds_read_b128 v[190:193], v248 offset:1024
	v_mfma_f32_16x16x32_bf16 v[132:135], v[16:19], v[12:15], v[132:135]
	ds_read_b128 v[216:219], v249 offset:9216
	v_mfma_f32_16x16x32_bf16 v[116:119], v[20:23], v[0:3], v[116:119]
	ds_read_b128 v[194:197], v248 offset:2048
	v_mfma_f32_16x16x32_bf16 v[92:95], v[20:23], v[4:7], v[92:95]
	ds_read_b128 v[220:223], v249 offset:10240
	v_mfma_f32_16x16x32_bf16 v[112:115], v[20:23], v[8:11], v[112:115]
	ds_read_b128 v[208:211], v248 offset:3072
	v_mfma_f32_16x16x32_bf16 v[136:139], v[20:23], v[12:15], v[136:139]
	ds_read_b128 v[224:227], v249 offset:11264
	v_mfma_f32_16x16x32_bf16 v[104:107], v[162:165], v[0:3], v[104:107]
	ds_read_b128 v[228:231], v249 offset:12288
	v_mfma_f32_16x16x32_bf16 v[88:91], v[162:165], v[4:7], v[88:91]
	ds_read_b128 v[232:235], v249 offset:13312
	v_mfma_f32_16x16x32_bf16 v[120:123], v[162:165], v[8:11], v[120:123]
	ds_read_b128 v[236:239], v249 offset:14336
	v_mfma_f32_16x16x32_bf16 v[140:143], v[162:165], v[12:15], v[140:143]
	ds_read_b128 v[240:243], v249 offset:15360
	s_add_u32 m0, s25, s24
	v_mfma_f32_16x16x32_bf16 v[100:103], v[166:169], v[0:3], v[100:103]
	global_load_lds_dwordx4 v156, s[26:27]
	v_mfma_f32_16x16x32_bf16 v[84:87], v[166:169], v[4:7], v[84:87]
	v_mfma_f32_16x16x32_bf16 v[124:127], v[166:169], v[8:11], v[124:127]
	s_add_u32 m0, m0, 0x1000
	v_mfma_f32_16x16x32_bf16 v[144:147], v[166:169], v[12:15], v[144:147]
	global_load_lds_dwordx4 v157, s[26:27]
	v_mfma_f32_16x16x32_bf16 v[52:55], v[170:173], v[0:3], v[52:55]
	v_mfma_f32_16x16x32_bf16 v[36:39], v[170:173], v[4:7], v[36:39]
	s_add_u32 m0, m0, 0x1000
	v_mfma_f32_16x16x32_bf16 v[64:67], v[170:173], v[8:11], v[64:67]
	global_load_lds_dwordx4 v156, s[28:29]
	v_mfma_f32_16x16x32_bf16 v[76:79], v[170:173], v[12:15], v[76:79]
	v_mfma_f32_16x16x32_bf16 v[48:51], v[174:177], v[0:3], v[48:51]
	s_add_u32 m0, m0, 0x1000
	v_mfma_f32_16x16x32_bf16 v[32:35], v[174:177], v[4:7], v[32:35]
	global_load_lds_dwordx4 v157, s[28:29]
	v_mfma_f32_16x16x32_bf16 v[68:71], v[174:177], v[8:11], v[68:71]
	v_mfma_f32_16x16x32_bf16 v[72:75], v[174:177], v[12:15], v[72:75]
	s_add_u32 m0, m0, 0x1000
	v_mfma_f32_16x16x32_bf16 v[44:47], v[178:181], v[0:3], v[44:47]
	global_load_lds_dwordx4 v158, s[28:29]
	v_mfma_f32_16x16x32_bf16 v[28:31], v[178:181], v[4:7], v[28:31]
	v_mfma_f32_16x16x32_bf16 v[80:83], v[178:181], v[8:11], v[80:83]
	s_add_u32 m0, m0, 0x1000
	v_mfma_f32_16x16x32_bf16 v[60:63], v[178:181], v[12:15], v[60:63]
	global_load_lds_dwordx4 v159, s[28:29]
	v_mfma_f32_16x16x32_bf16 v[40:43], v[182:185], v[0:3], v[40:43]
	v_mfma_f32_16x16x32_bf16 v[24:27], v[182:185], v[4:7], v[24:27]
	v_mfma_f32_16x16x32_bf16 v[56:59], v[182:185], v[8:11], v[56:59]
	v_mfma_f32_16x16x32_bf16 v[148:151], v[182:185], v[12:15], v[148:151]
	s_add_u32 s26, s26, 0x200000
	s_addc_u32 s27, s27, 0
	s_add_u32 s28, s28, 0x40000
	s_addc_u32 s29, s29, 0
	s_add_u32 s25, s25, 24576
	s_cmp_eq_u32 s25, 73728
	s_cselect_b32 s25, 0, s25
	s_add_u32 s30, s30, 24576
	s_cmp_eq_u32 s30, 73728
	s_cselect_b32 s30, 0, s30
	s_waitcnt vmcnt(6)
	s_waitcnt lgkmcnt(0)
	s_barrier
	s_sub_u32 s31, s31, 1
	s_cmp_lg_u32 s31, 0
	s_cbranch_scc1 .Lgm0_loop
	v_add_u32_e32 v248, s30, v155
	v_add_u32_e32 v249, s30, v160
	v_mfma_f32_16x16x32_bf16 v[128:131], v[212:215], v[186:189], v[128:131]
	ds_read_b128 v[0:3], v248
	v_mfma_f32_16x16x32_bf16 v[96:99], v[212:215], v[190:193], v[96:99]
	ds_read_b128 v[16:19], v249 offset:8192
	v_mfma_f32_16x16x32_bf16 v[108:111], v[212:215], v[194:197], v[108:111]
	ds_read_b128 v[4:7], v248 offset:1024
	v_mfma_f32_16x16x32_bf16 v[132:135], v[212:215], v[208:211], v[132:135]
	ds_read_b128 v[20:23], v249 offset:9216
	v_mfma_f32_16x16x32_bf16 v[116:119], v[216:219], v[186:189], v[116:119]
	ds_read_b128 v[8:11], v248 offset:2048
	v_mfma_f32_16x16x32_bf16 v[92:95], v[216:219], v[190:193], v[92:95]
	ds_read_b128 v[162:165], v249 offset:10240
	v_mfma_f32_16x16x32_bf16 v[112:115], v[216:219], v[194:197], v[112:115]
	ds_read_b128 v[12:15], v248 offset:3072
	v_mfma_f32_16x16x32_bf16 v[136:139], v[216:219], v[208:211], v[136:139]
	ds_read_b128 v[166:169], v249 offset:11264
	v_mfma_f32_16x16x32_bf16 v[104:107], v[220:223], v[186:189], v[104:107]
	ds_read_b128 v[170:173], v249 offset:12288
	v_mfma_f32_16x16x32_bf16 v[88:91], v[220:223], v[190:193], v[88:91]
	ds_read_b128 v[174:177], v249 offset:13312
	v_mfma_f32_16x16x32_bf16 v[120:123], v[220:223], v[194:197], v[120:123]
	ds_read_b128 v[178:181], v249 offset:14336
	v_mfma_f32_16x16x32_bf16 v[140:143], v[220:223], v[208:211], v[140:143]
	ds_read_b128 v[182:185], v249 offset:15360
	s_add_u32 m0, s25, s24
	v_mfma_f32_16x16x32_bf16 v[100:103], v[224:227], v[186:189], v[100:103]
	global_load_lds_dwordx4 v156, s[26:27]
	v_mfma_f32_16x16x32_bf16 v[84:87], v[224:227], v[190:193], v[84:87]
	v_mfma_f32_16x16x32_bf16 v[124:127], v[224:227], v[194:197], v[124:127]
	s_add_u32 m0, m0, 0x1000
	v_mfma_f32_16x16x32_bf16 v[144:147], v[224:227], v[208:211], v[144:147]
	global_load_lds_dwordx4 v157, s[26:27]
	v_mfma_f32_16x16x32_bf16 v[52:55], v[228:231], v[186:189], v[52:55]
	v_mfma_f32_16x16x32_bf16 v[36:39], v[228:231], v[190:193], v[36:39]
	s_add_u32 m0, m0, 0x1000
	v_mfma_f32_16x16x32_bf16 v[64:67], v[228:231], v[194:197], v[64:67]
	global_load_lds_dwordx4 v156, s[28:29]
	v_mfma_f32_16x16x32_bf16 v[76:79], v[228:231], v[208:211], v[76:79]
	v_mfma_f32_16x16x32_bf16 v[48:51], v[232:235], v[186:189], v[48:51]
	s_add_u32 m0, m0, 0x1000
	v_mfma_f32_16x16x32_bf16 v[32:35], v[232:235], v[190:193], v[32:35]
	global_load_lds_dwordx4 v157, s[28:29]
	v_mfma_f32_16x16x32_bf16 v[68:71], v[232:235], v[194:197], v[68:71]
	v_mfma_f32_16x16x32_bf16 v[72:75], v[232:235], v[208:211], v[72:75]
	s_add_u32 m0, m0, 0x1000
	v_mfma_f32_16x16x32_bf16 v[44:47], v[236:239], v[186:189], v[44:47]
	global_load_lds_dwordx4 v158, s[28:29]
	v_mfma_f32_16x16x32_bf16 v[28:31], v[236:239], v[190:193], v[28:31]
	v_mfma_f32_16x16x32_bf16 v[80:83], v[236:239], v[194:197], v[80:83]
	s_add_u32 m0, m0, 0x1000
	v_mfma_f32_16x16x32_bf16 v[60:63], v[236:239], v[208:211], v[60:63]
	global_load_lds_dwordx4 v159, s[28:29]
	v_mfma_f32_16x16x32_bf16 v[40:43], v[240:243], v[186:189], v[40:43]
	v_mfma_f32_16x16x32_bf16 v[24:27], v[240:243], v[190:193], v[24:27]
	v_mfma_f32_16x16x32_bf16 v[56:59], v[240:243], v[194:197], v[56:59]
	v_mfma_f32_16x16x32_bf16 v[148:151], v[240:243], v[208:211], v[148:151]
	s_add_u32 s26, s26, 0x200000
	s_addc_u32 s27, s27, 0
	s_add_u32 s28, s28, 0x40000
	s_addc_u32 s29, s29, 0
	s_add_u32 s25, s25, 24576
	s_cmp_eq_u32 s25, 73728
	s_cselect_b32 s25, 0, s25
	s_add_u32 s30, s30, 24576
	s_cmp_eq_u32 s30, 73728
	s_cselect_b32 s30, 0, s30
	s_waitcnt vmcnt(6)
	s_waitcnt lgkmcnt(0)
	s_barrier
	v_add_u32_e32 v248, s30, v155
	v_add_u32_e32 v249, s30, v160
	v_mfma_f32_16x16x32_bf16 v[128:131], v[16:19], v[0:3], v[128:131]
	ds_read_b128 v[186:189], v248
	v_mfma_f32_16x16x32_bf16 v[96:99], v[16:19], v[4:7], v[96:99]
	ds_read_b128 v[212:215], v249 offset:8192
	v_mfma_f32_16x16x32_bf16 v[108:111], v[16:19], v[8:11], v[108:111]
	ds_read_b128 v[190:193], v248 offset:1024
	v_mfma_f32_16x16x32_bf16 v[132:135], v[16:19], v[12:15], v[132:135]
	ds_read_b128 v[216:219], v249 offset:9216
	v_mfma_f32_16x16x32_bf16 v[116:119], v[20:23], v[0:3], v[116:119]
	ds_read_b128 v[194:197], v248 offset:2048
	v_mfma_f32_16x16x32_bf16 v[92:95], v[20:23], v[4:7], v[92:95]
	ds_read_b128 v[220:223], v249 offset:10240
	v_mfma_f32_16x16x32_bf16 v[112:115], v[20:23], v[8:11], v[112:115]
	ds_read_b128 v[208:211], v248 offset:3072
	v_mfma_f32_16x16x32_bf16 v[136:139], v[20:23], v[12:15], v[136:139]
	ds_read_b128 v[224:227], v249 offset:11264
	v_mfma_f32_16x16x32_bf16 v[104:107], v[162:165], v[0:3], v[104:107]
	ds_read_b128 v[228:231], v249 offset:12288
	v_mfma_f32_16x16x32_bf16 v[88:91], v[162:165], v[4:7], v[88:91]
	ds_read_b128 v[232:235], v249 offset:13312
	v_mfma_f32_16x16x32_bf16 v[120:123], v[162:165], v[8:11], v[120:123]
	ds_read_b128 v[236:239], v249 offset:14336
	v_mfma_f32_16x16x32_bf16 v[140:143], v[162:165], v[12:15], v[140:143]
	ds_read_b128 v[240:243], v249 offset:15360
	v_mfma_f32_16x16x32_bf16 v[100:103], v[166:169], v[0:3], v[100:103]
	v_mfma_f32_16x16x32_bf16 v[84:87], v[166:169], v[4:7], v[84:87]
	v_mfma_f32_16x16x32_bf16 v[124:127], v[166:169], v[8:11], v[124:127]
	v_mfma_f32_16x16x32_bf16 v[144:147], v[166:169], v[12:15], v[144:147]
	v_mfma_f32_16x16x32_bf16 v[52:55], v[170:173], v[0:3], v[52:55]
	v_mfma_f32_16x16x32_bf16 v[36:39], v[170:173], v[4:7], v[36:39]
	v_mfma_f32_16x16x32_bf16 v[64:67], v[170:173], v[8:11], v[64:67]
	v_mfma_f32_16x16x32_bf16 v[76:79], v[170:173], v[12:15], v[76:79]
	v_mfma_f32_16x16x32_bf16 v[48:51], v[174:177], v[0:3], v[48:51]
	v_mfma_f32_16x16x32_bf16 v[32:35], v[174:177], v[4:7], v[32:35]
	v_mfma_f32_16x16x32_bf16 v[68:71], v[174:177], v[8:11], v[68:71]
	v_mfma_f32_16x16x32_bf16 v[72:75], v[174:177], v[12:15], v[72:75]
	v_mfma_f32_16x16x32_bf16 v[44:47], v[178:181], v[0:3], v[44:47]
	v_mfma_f32_16x16x32_bf16 v[28:31], v[178:181], v[4:7], v[28:31]
	v_mfma_f32_16x16x32_bf16 v[80:83], v[178:181], v[8:11], v[80:83]
	v_mfma_f32_16x16x32_bf16 v[60:63], v[178:181], v[12:15], v[60:63]
	v_mfma_f32_16x16x32_bf16 v[40:43], v[182:185], v[0:3], v[40:43]
	v_mfma_f32_16x16x32_bf16 v[24:27], v[182:185], v[4:7], v[24:27]
	v_mfma_f32_16x16x32_bf16 v[56:59], v[182:185], v[8:11], v[56:59]
	v_mfma_f32_16x16x32_bf16 v[148:151], v[182:185], v[12:15], v[148:151]
	s_add_u32 s30, s30, 24576
	s_cmp_eq_u32 s30, 73728
	s_cselect_b32 s30, 0, s30
	s_waitcnt vmcnt(0)
	s_waitcnt lgkmcnt(0)
	s_barrier
	v_add_u32_e32 v248, s30, v155
	v_add_u32_e32 v249, s30, v160
	v_mfma_f32_16x16x32_bf16 v[128:131], v[212:215], v[186:189], v[128:131]
	ds_read_b128 v[0:3], v248
	v_mfma_f32_16x16x32_bf16 v[96:99], v[212:215], v[190:193], v[96:99]
	ds_read_b128 v[16:19], v249 offset:8192
	v_mfma_f32_16x16x32_bf16 v[108:111], v[212:215], v[194:197], v[108:111]
	ds_read_b128 v[4:7], v248 offset:1024
	v_mfma_f32_16x16x32_bf16 v[132:135], v[212:215], v[208:211], v[132:135]
	ds_read_b128 v[20:23], v249 offset:9216
	v_mfma_f32_16x16x32_bf16 v[116:119], v[216:219], v[186:189], v[116:119]
	ds_read_b128 v[8:11], v248 offset:2048
	v_mfma_f32_16x16x32_bf16 v[92:95], v[216:219], v[190:193], v[92:95]
	ds_read_b128 v[162:165], v249 offset:10240
	v_mfma_f32_16x16x32_bf16 v[112:115], v[216:219], v[194:197], v[112:115]
	ds_read_b128 v[12:15], v248 offset:3072
	v_mfma_f32_16x16x32_bf16 v[136:139], v[216:219], v[208:211], v[136:139]
	ds_read_b128 v[166:169], v249 offset:11264
	v_mfma_f32_16x16x32_bf16 v[104:107], v[220:223], v[186:189], v[104:107]
	ds_read_b128 v[170:173], v249 offset:12288
	v_mfma_f32_16x16x32_bf16 v[88:91], v[220:223], v[190:193], v[88:91]
	ds_read_b128 v[174:177], v249 offset:13312
	v_mfma_f32_16x16x32_bf16 v[120:123], v[220:223], v[194:197], v[120:123]
	ds_read_b128 v[178:181], v249 offset:14336
	v_mfma_f32_16x16x32_bf16 v[140:143], v[220:223], v[208:211], v[140:143]
	ds_read_b128 v[182:185], v249 offset:15360
	v_mfma_f32_16x16x32_bf16 v[100:103], v[224:227], v[186:189], v[100:103]
	v_mfma_f32_16x16x32_bf16 v[84:87], v[224:227], v[190:193], v[84:87]
	v_mfma_f32_16x16x32_bf16 v[124:127], v[224:227], v[194:197], v[124:127]
	v_mfma_f32_16x16x32_bf16 v[144:147], v[224:227], v[208:211], v[144:147]
	v_mfma_f32_16x16x32_bf16 v[52:55], v[228:231], v[186:189], v[52:55]
	v_mfma_f32_16x16x32_bf16 v[36:39], v[228:231], v[190:193], v[36:39]
	v_mfma_f32_16x16x32_bf16 v[64:67], v[228:231], v[194:197], v[64:67]
	v_mfma_f32_16x16x32_bf16 v[76:79], v[228:231], v[208:211], v[76:79]
	v_mfma_f32_16x16x32_bf16 v[48:51], v[232:235], v[186:189], v[48:51]
	v_mfma_f32_16x16x32_bf16 v[32:35], v[232:235], v[190:193], v[32:35]
	v_mfma_f32_16x16x32_bf16 v[68:71], v[232:235], v[194:197], v[68:71]
	v_mfma_f32_16x16x32_bf16 v[72:75], v[232:235], v[208:211], v[72:75]
	v_mfma_f32_16x16x32_bf16 v[44:47], v[236:239], v[186:189], v[44:47]
	v_mfma_f32_16x16x32_bf16 v[28:31], v[236:239], v[190:193], v[28:31]
	v_mfma_f32_16x16x32_bf16 v[80:83], v[236:239], v[194:197], v[80:83]
	v_mfma_f32_16x16x32_bf16 v[60:63], v[236:239], v[208:211], v[60:63]
	v_mfma_f32_16x16x32_bf16 v[40:43], v[240:243], v[186:189], v[40:43]
	v_mfma_f32_16x16x32_bf16 v[24:27], v[240:243], v[190:193], v[24:27]
	v_mfma_f32_16x16x32_bf16 v[56:59], v[240:243], v[194:197], v[56:59]
	v_mfma_f32_16x16x32_bf16 v[148:151], v[240:243], v[208:211], v[148:151]
	s_add_u32 s30, s30, 24576
	s_cmp_eq_u32 s30, 73728
	s_cselect_b32 s30, 0, s30
	s_waitcnt lgkmcnt(0)
	s_barrier
	v_mfma_f32_16x16x32_bf16 v[128:131], v[16:19], v[0:3], v[128:131]
	v_mfma_f32_16x16x32_bf16 v[96:99], v[16:19], v[4:7], v[96:99]
	v_mfma_f32_16x16x32_bf16 v[108:111], v[16:19], v[8:11], v[108:111]
	v_mfma_f32_16x16x32_bf16 v[132:135], v[16:19], v[12:15], v[132:135]
	v_mfma_f32_16x16x32_bf16 v[116:119], v[20:23], v[0:3], v[116:119]
	v_mfma_f32_16x16x32_bf16 v[92:95], v[20:23], v[4:7], v[92:95]
	v_mfma_f32_16x16x32_bf16 v[112:115], v[20:23], v[8:11], v[112:115]
	v_mfma_f32_16x16x32_bf16 v[136:139], v[20:23], v[12:15], v[136:139]
	v_mfma_f32_16x16x32_bf16 v[104:107], v[162:165], v[0:3], v[104:107]
	v_mfma_f32_16x16x32_bf16 v[88:91], v[162:165], v[4:7], v[88:91]
	v_mfma_f32_16x16x32_bf16 v[120:123], v[162:165], v[8:11], v[120:123]
	v_mfma_f32_16x16x32_bf16 v[140:143], v[162:165], v[12:15], v[140:143]
	v_mfma_f32_16x16x32_bf16 v[100:103], v[166:169], v[0:3], v[100:103]
	v_mfma_f32_16x16x32_bf16 v[84:87], v[166:169], v[4:7], v[84:87]
	v_mfma_f32_16x16x32_bf16 v[124:127], v[166:169], v[8:11], v[124:127]
	v_mfma_f32_16x16x32_bf16 v[144:147], v[166:169], v[12:15], v[144:147]
	v_mfma_f32_16x16x32_bf16 v[52:55], v[170:173], v[0:3], v[52:55]
	v_mfma_f32_16x16x32_bf16 v[36:39], v[170:173], v[4:7], v[36:39]
	v_mfma_f32_16x16x32_bf16 v[64:67], v[170:173], v[8:11], v[64:67]
	v_mfma_f32_16x16x32_bf16 v[76:79], v[170:173], v[12:15], v[76:79]
	v_mfma_f32_16x16x32_bf16 v[48:51], v[174:177], v[0:3], v[48:51]
	v_mfma_f32_16x16x32_bf16 v[32:35], v[174:177], v[4:7], v[32:35]
	v_mfma_f32_16x16x32_bf16 v[68:71], v[174:177], v[8:11], v[68:71]
	v_mfma_f32_16x16x32_bf16 v[72:75], v[174:177], v[12:15], v[72:75]
	v_mfma_f32_16x16x32_bf16 v[44:47], v[178:181], v[0:3], v[44:47]
	v_mfma_f32_16x16x32_bf16 v[28:31], v[178:181], v[4:7], v[28:31]
	v_mfma_f32_16x16x32_bf16 v[80:83], v[178:181], v[8:11], v[80:83]
	v_mfma_f32_16x16x32_bf16 v[60:63], v[178:181], v[12:15], v[60:63]
	v_mfma_f32_16x16x32_bf16 v[40:43], v[182:185], v[0:3], v[40:43]
	v_mfma_f32_16x16x32_bf16 v[24:27], v[182:185], v[4:7], v[24:27]
	v_mfma_f32_16x16x32_bf16 v[56:59], v[182:185], v[8:11], v[56:59]
	v_mfma_f32_16x16x32_bf16 v[148:151], v[182:185], v[12:15], v[148:151]
	s_add_i32 s12, s12, s6
	s_add_i32 s11, s11, s9
	s_add_i32 s10, s10, s6
	s_cmpk_gt_u32 s12, 0x1ff
	s_cselect_b32 s23, 1, 0
	v_mov_b32 v250, v198
	s_nop 0
	v_and_b32_e32 v251, 15, v250
	v_bfe_u32 v156, v250, 4, 2
	v_bfe_u32 v157, v250, 6, 1
	v_bfe_u32 v158, v250, 7, 1
	v_lshl_add_u32 v158, v158, 6, s14
	v_add_u32_e32 v158, v158, v251
	v_lshl_add_u32 v157, v157, 7, s13
	v_lshl_add_u32 v159, v156, 2, v157
	v_lshlrev_b32_e32 v230, 6, v158
	v_lshrrev_b32_e32 v228, 5, v157
	v_lshlrev_b32_e32 v228, 21, v228
	v_lshl_add_u32 v228, v158, 6, v228
	v_lshl_add_u32 v228, v156, 3, v228
	v_and_b32_e32 v161, 1, v156
	v_mul_u32_u24_e32 v161, 24, v161
	v_add_u32_e32 v229, v228, v161
	s_mov_b32 s30, s92
	s_mov_b32 s31, s93
	global_load_dwordx4 v[0:3], v230, s[94:95]
	global_load_dwordx4 v[4:7], v230, s[94:95] offset:16
	global_load_dwordx4 v[8:11], v230, s[94:95] offset:32
	global_load_dwordx4 v[12:15], v230, s[94:95] offset:48
	global_load_dwordx4 v[16:19], v230, s[94:95] offset:1024
	global_load_dwordx4 v[20:23], v230, s[94:95] offset:1040
	global_load_dwordx4 v[162:165], v230, s[94:95] offset:1056
	global_load_dwordx4 v[166:169], v230, s[94:95] offset:1072
	global_load_dwordx4 v[170:173], v230, s[94:95] offset:2048
	global_load_dwordx4 v[174:177], v230, s[94:95] offset:2064
	global_load_dwordx4 v[178:181], v230, s[94:95] offset:2080
	global_load_dwordx4 v[182:185], v230, s[94:95] offset:2096
	global_load_dwordx4 v[186:189], v230, s[94:95] offset:3072
	global_load_dwordx4 v[190:193], v230, s[94:95] offset:3088
	global_load_dwordx4 v[194:197], v230, s[94:95] offset:3104
	global_load_dwordx4 v[208:211], v230, s[94:95] offset:3120
	s_waitcnt vmcnt(12)
	v_add_f32_e32 v231, v0, v1
	v_add_f32_e32 v248, v2, v3
	v_add_f32_e32 v231, v231, v248
	v_add_f32_e32 v249, v4, v5
	v_add_f32_e32 v248, v6, v7
	v_add_f32_e32 v249, v249, v248
	v_add_f32_e32 v231, v231, v249
	v_add_f32_e32 v249, v8, v9
	v_add_f32_e32 v248, v10, v11
	v_add_f32_e32 v249, v249, v248
	v_add_f32_e32 v231, v231, v249
	v_add_f32_e32 v249, v12, v13
	v_add_f32_e32 v248, v14, v15
	v_add_f32_e32 v249, v249, v248
	v_add_f32_e32 v231, v231, v249
	v_fmamk_f32 v231, v231, 0x3a800000, v199
	v_cmp_gt_f32_e32 vcc, s73, v231
	v_mul_f32_e32 v248, 0x4b800000, v231
	s_nop 0
	v_cndmask_b32_e32 v231, v231, v248, vcc
	v_rsq_f32_e32 v231, v231
	s_nop 0
	v_mul_f32_e32 v248, 0x45800000, v231
	v_cndmask_b32_e32 v231, v231, v248, vcc
	v_mul_f32_e32 v212, v128, v231
	v_mul_f32_e32 v249, v129, v231
	v_mul_f32_e32 v213, v130, v231
	v_mul_f32_e32 v248, v131, v231
	v_max_f32_e32 v212, 0, v212
	v_max_f32_e32 v249, 0, v249
	v_max_f32_e32 v213, 0, v213
	v_max_f32_e32 v248, 0, v248
	v_mul_f32_e32 v212, v212, v212
	v_mul_f32_e32 v249, v249, v249
	v_mul_f32_e32 v213, v213, v213
	v_mul_f32_e32 v248, v248, v248
	v_cvt_pk_bf16_f32 v212, v212, v249
	v_cvt_pk_bf16_f32 v213, v213, v248
	v_mul_f32_e32 v214, v116, v231
	v_mul_f32_e32 v249, v117, v231
	v_mul_f32_e32 v215, v118, v231
	v_mul_f32_e32 v248, v119, v231
	v_max_f32_e32 v214, 0, v214
	v_max_f32_e32 v249, 0, v249
	v_max_f32_e32 v215, 0, v215
	v_max_f32_e32 v248, 0, v248
	v_mul_f32_e32 v214, v214, v214
	v_mul_f32_e32 v249, v249, v249
	v_mul_f32_e32 v215, v215, v215
	v_mul_f32_e32 v248, v248, v248
	v_cvt_pk_bf16_f32 v214, v214, v249
	v_cvt_pk_bf16_f32 v215, v215, v248
	s_add_u32 s30, s92, 0x0
	s_addc_u32 s31, s93, 0
	s_nop 0
	v_permlane16_swap_b32_e32 v212, v214
	v_permlane16_swap_b32_e32 v213, v215
	global_store_dwordx4 v229, v[212:215], s[30:31]
	v_mul_f32_e32 v216, v104, v231
	v_mul_f32_e32 v249, v105, v231
	v_mul_f32_e32 v217, v106, v231
	v_mul_f32_e32 v248, v107, v231
	v_max_f32_e32 v216, 0, v216
	v_max_f32_e32 v249, 0, v249
	v_max_f32_e32 v217, 0, v217
	v_max_f32_e32 v248, 0, v248
	v_mul_f32_e32 v216, v216, v216
	v_mul_f32_e32 v249, v249, v249
	v_mul_f32_e32 v217, v217, v217
	v_mul_f32_e32 v248, v248, v248
	v_cvt_pk_bf16_f32 v216, v216, v249
	v_cvt_pk_bf16_f32 v217, v217, v248
	v_mul_f32_e32 v218, v100, v231
	v_mul_f32_e32 v249, v101, v231
	v_mul_f32_e32 v219, v102, v231
	v_mul_f32_e32 v248, v103, v231
	v_max_f32_e32 v218, 0, v218
	v_max_f32_e32 v249, 0, v249
	v_max_f32_e32 v219, 0, v219
	v_max_f32_e32 v248, 0, v248
	v_mul_f32_e32 v218, v218, v218
	v_mul_f32_e32 v249, v249, v249
	v_mul_f32_e32 v219, v219, v219
	v_mul_f32_e32 v248, v248, v248
	v_cvt_pk_bf16_f32 v218, v218, v249
	v_cvt_pk_bf16_f32 v219, v219, v248
	s_add_u32 s30, s92, 0x200000
	s_addc_u32 s31, s93, 0
	s_nop 0
	v_permlane16_swap_b32_e32 v216, v218
	v_permlane16_swap_b32_e32 v217, v219
	global_store_dwordx4 v229, v[216:219], s[30:31]
	v_mul_f32_e32 v220, v52, v231
	v_mul_f32_e32 v249, v53, v231
	v_mul_f32_e32 v221, v54, v231
	v_mul_f32_e32 v248, v55, v231
	v_max_f32_e32 v220, 0, v220
	v_max_f32_e32 v249, 0, v249
	v_max_f32_e32 v221, 0, v221
	v_max_f32_e32 v248, 0, v248
	v_mul_f32_e32 v220, v220, v220
	v_mul_f32_e32 v249, v249, v249
	v_mul_f32_e32 v221, v221, v221
	v_mul_f32_e32 v248, v248, v248
	v_cvt_pk_bf16_f32 v220, v220, v249
	v_cvt_pk_bf16_f32 v221, v221, v248
	v_mul_f32_e32 v222, v48, v231
	v_mul_f32_e32 v249, v49, v231
	v_mul_f32_e32 v223, v50, v231
	v_mul_f32_e32 v248, v51, v231
	v_max_f32_e32 v222, 0, v222
	v_max_f32_e32 v249, 0, v249
	v_max_f32_e32 v223, 0, v223
	v_max_f32_e32 v248, 0, v248
	v_mul_f32_e32 v222, v222, v222
	v_mul_f32_e32 v249, v249, v249
	v_mul_f32_e32 v223, v223, v223
	v_mul_f32_e32 v248, v248, v248
	v_cvt_pk_bf16_f32 v222, v222, v249
	v_cvt_pk_bf16_f32 v223, v223, v248
	s_add_u32 s30, s92, 0x400000
	s_addc_u32 s31, s93, 0
	s_nop 0
	v_permlane16_swap_b32_e32 v220, v222
	v_permlane16_swap_b32_e32 v221, v223
	global_store_dwordx4 v229, v[220:223], s[30:31]
	v_mul_f32_e32 v224, v44, v231
	v_mul_f32_e32 v249, v45, v231
	v_mul_f32_e32 v225, v46, v231
	v_mul_f32_e32 v248, v47, v231
	v_max_f32_e32 v224, 0, v224
	v_max_f32_e32 v249, 0, v249
	v_max_f32_e32 v225, 0, v225
	v_max_f32_e32 v248, 0, v248
	v_mul_f32_e32 v224, v224, v224
	v_mul_f32_e32 v249, v249, v249
	v_mul_f32_e32 v225, v225, v225
	v_mul_f32_e32 v248, v248, v248
	v_cvt_pk_bf16_f32 v224, v224, v249
	v_cvt_pk_bf16_f32 v225, v225, v248
	v_mul_f32_e32 v226, v40, v231
	v_mul_f32_e32 v249, v41, v231
	v_mul_f32_e32 v227, v42, v231
	v_mul_f32_e32 v248, v43, v231
	v_max_f32_e32 v226, 0, v226
	v_max_f32_e32 v249, 0, v249
	v_max_f32_e32 v227, 0, v227
	v_max_f32_e32 v248, 0, v248
	v_mul_f32_e32 v226, v226, v226
	v_mul_f32_e32 v249, v249, v249
	v_mul_f32_e32 v227, v227, v227
	v_mul_f32_e32 v248, v248, v248
	v_cvt_pk_bf16_f32 v226, v226, v249
	v_cvt_pk_bf16_f32 v227, v227, v248
	s_add_u32 s30, s92, 0x600000
	s_addc_u32 s31, s93, 0
	s_nop 0
	v_permlane16_swap_b32_e32 v224, v226
	v_permlane16_swap_b32_e32 v225, v227
	global_store_dwordx4 v229, v[224:227], s[30:31]
	s_waitcnt vmcnt(12)
	v_add_f32_e32 v231, v16, v17
	v_add_f32_e32 v248, v18, v19
	v_add_f32_e32 v231, v231, v248
	v_add_f32_e32 v249, v20, v21
	v_add_f32_e32 v248, v22, v23
	v_add_f32_e32 v249, v249, v248
	v_add_f32_e32 v231, v231, v249
	v_add_f32_e32 v249, v162, v163
	v_add_f32_e32 v248, v164, v165
	v_add_f32_e32 v249, v249, v248
	v_add_f32_e32 v231, v231, v249
	v_add_f32_e32 v249, v166, v167
	v_add_f32_e32 v248, v168, v169
	v_add_f32_e32 v249, v249, v248
	v_add_f32_e32 v231, v231, v249
	v_fmamk_f32 v231, v231, 0x3a800000, v199
	v_cmp_gt_f32_e32 vcc, s73, v231
	v_mul_f32_e32 v248, 0x4b800000, v231
	s_nop 0
	v_cndmask_b32_e32 v231, v231, v248, vcc
	v_rsq_f32_e32 v231, v231
	s_nop 0
	v_mul_f32_e32 v248, 0x45800000, v231
	v_cndmask_b32_e32 v231, v231, v248, vcc
	v_mul_f32_e32 v212, v96, v231
	v_mul_f32_e32 v249, v97, v231
	v_mul_f32_e32 v213, v98, v231
	v_mul_f32_e32 v248, v99, v231
	v_max_f32_e32 v212, 0, v212
	v_max_f32_e32 v249, 0, v249
	v_max_f32_e32 v213, 0, v213
	v_max_f32_e32 v248, 0, v248
	v_mul_f32_e32 v212, v212, v212
	v_mul_f32_e32 v249, v249, v249
	v_mul_f32_e32 v213, v213, v213
	v_mul_f32_e32 v248, v248, v248
	v_cvt_pk_bf16_f32 v212, v212, v249
	v_cvt_pk_bf16_f32 v213, v213, v248
	v_mul_f32_e32 v214, v92, v231
	v_mul_f32_e32 v249, v93, v231
	v_mul_f32_e32 v215, v94, v231
	v_mul_f32_e32 v248, v95, v231
	v_max_f32_e32 v214, 0, v214
	v_max_f32_e32 v249, 0, v249
	v_max_f32_e32 v215, 0, v215
	v_max_f32_e32 v248, 0, v248
	v_mul_f32_e32 v214, v214, v214
	v_mul_f32_e32 v249, v249, v249
	v_mul_f32_e32 v215, v215, v215
	v_mul_f32_e32 v248, v248, v248
	v_cvt_pk_bf16_f32 v214, v214, v249
	v_cvt_pk_bf16_f32 v215, v215, v248
	s_add_u32 s30, s92, 0x400
	s_addc_u32 s31, s93, 0
	s_nop 0
	v_permlane16_swap_b32_e32 v212, v214
	v_permlane16_swap_b32_e32 v213, v215
	global_store_dwordx4 v229, v[212:215], s[30:31]
	v_mul_f32_e32 v216, v88, v231
	v_mul_f32_e32 v249, v89, v231
	v_mul_f32_e32 v217, v90, v231
	v_mul_f32_e32 v248, v91, v231
	v_max_f32_e32 v216, 0, v216
	v_max_f32_e32 v249, 0, v249
	v_max_f32_e32 v217, 0, v217
	v_max_f32_e32 v248, 0, v248
	v_mul_f32_e32 v216, v216, v216
	v_mul_f32_e32 v249, v249, v249
	v_mul_f32_e32 v217, v217, v217
	v_mul_f32_e32 v248, v248, v248
	v_cvt_pk_bf16_f32 v216, v216, v249
	v_cvt_pk_bf16_f32 v217, v217, v248
	v_mul_f32_e32 v218, v84, v231
	v_mul_f32_e32 v249, v85, v231
	v_mul_f32_e32 v219, v86, v231
	v_mul_f32_e32 v248, v87, v231
	v_max_f32_e32 v218, 0, v218
	v_max_f32_e32 v249, 0, v249
	v_max_f32_e32 v219, 0, v219
	v_max_f32_e32 v248, 0, v248
	v_mul_f32_e32 v218, v218, v218
	v_mul_f32_e32 v249, v249, v249
	v_mul_f32_e32 v219, v219, v219
	v_mul_f32_e32 v248, v248, v248
	v_cvt_pk_bf16_f32 v218, v218, v249
	v_cvt_pk_bf16_f32 v219, v219, v248
	s_add_u32 s30, s92, 0x200400
	s_addc_u32 s31, s93, 0
	s_nop 0
	v_permlane16_swap_b32_e32 v216, v218
	v_permlane16_swap_b32_e32 v217, v219
	global_store_dwordx4 v229, v[216:219], s[30:31]
	v_mul_f32_e32 v220, v36, v231
	v_mul_f32_e32 v249, v37, v231
	v_mul_f32_e32 v221, v38, v231
	v_mul_f32_e32 v248, v39, v231
	v_max_f32_e32 v220, 0, v220
	v_max_f32_e32 v249, 0, v249
	v_max_f32_e32 v221, 0, v221
	v_max_f32_e32 v248, 0, v248
	v_mul_f32_e32 v220, v220, v220
	v_mul_f32_e32 v249, v249, v249
	v_mul_f32_e32 v221, v221, v221
	v_mul_f32_e32 v248, v248, v248
	v_cvt_pk_bf16_f32 v220, v220, v249
	v_cvt_pk_bf16_f32 v221, v221, v248
	v_mul_f32_e32 v222, v32, v231
	v_mul_f32_e32 v249, v33, v231
	v_mul_f32_e32 v223, v34, v231
	v_mul_f32_e32 v248, v35, v231
	v_max_f32_e32 v222, 0, v222
	v_max_f32_e32 v249, 0, v249
	v_max_f32_e32 v223, 0, v223
	v_max_f32_e32 v248, 0, v248
	v_mul_f32_e32 v222, v222, v222
	v_mul_f32_e32 v249, v249, v249
	v_mul_f32_e32 v223, v223, v223
	v_mul_f32_e32 v248, v248, v248
	v_cvt_pk_bf16_f32 v222, v222, v249
	v_cvt_pk_bf16_f32 v223, v223, v248
	s_add_u32 s30, s92, 0x400400
	s_addc_u32 s31, s93, 0
	s_nop 0
	v_permlane16_swap_b32_e32 v220, v222
	v_permlane16_swap_b32_e32 v221, v223
	global_store_dwordx4 v229, v[220:223], s[30:31]
	v_mul_f32_e32 v224, v28, v231
	v_mul_f32_e32 v249, v29, v231
	v_mul_f32_e32 v225, v30, v231
	v_mul_f32_e32 v248, v31, v231
	v_max_f32_e32 v224, 0, v224
	v_max_f32_e32 v249, 0, v249
	v_max_f32_e32 v225, 0, v225
	v_max_f32_e32 v248, 0, v248
	v_mul_f32_e32 v224, v224, v224
	v_mul_f32_e32 v249, v249, v249
	v_mul_f32_e32 v225, v225, v225
	v_mul_f32_e32 v248, v248, v248
	v_cvt_pk_bf16_f32 v224, v224, v249
	v_cvt_pk_bf16_f32 v225, v225, v248
	v_mul_f32_e32 v226, v24, v231
	v_mul_f32_e32 v249, v25, v231
	v_mul_f32_e32 v227, v26, v231
	v_mul_f32_e32 v248, v27, v231
	v_max_f32_e32 v226, 0, v226
	v_max_f32_e32 v249, 0, v249
	v_max_f32_e32 v227, 0, v227
	v_max_f32_e32 v248, 0, v248
	v_mul_f32_e32 v226, v226, v226
	v_mul_f32_e32 v249, v249, v249
	v_mul_f32_e32 v227, v227, v227
	v_mul_f32_e32 v248, v248, v248
	v_cvt_pk_bf16_f32 v226, v226, v249
	v_cvt_pk_bf16_f32 v227, v227, v248
	s_add_u32 s30, s92, 0x600400
	s_addc_u32 s31, s93, 0
	s_nop 0
	v_permlane16_swap_b32_e32 v224, v226
	v_permlane16_swap_b32_e32 v225, v227
	global_store_dwordx4 v229, v[224:227], s[30:31]
	s_waitcnt vmcnt(12)
	v_add_f32_e32 v231, v170, v171
	v_add_f32_e32 v248, v172, v173
	v_add_f32_e32 v231, v231, v248
	v_add_f32_e32 v249, v174, v175
	v_add_f32_e32 v248, v176, v177
	v_add_f32_e32 v249, v249, v248
	v_add_f32_e32 v231, v231, v249
	v_add_f32_e32 v249, v178, v179
	v_add_f32_e32 v248, v180, v181
	v_add_f32_e32 v249, v249, v248
	v_add_f32_e32 v231, v231, v249
	v_add_f32_e32 v249, v182, v183
	v_add_f32_e32 v248, v184, v185
	v_add_f32_e32 v249, v249, v248
	v_add_f32_e32 v231, v231, v249
	v_fmamk_f32 v231, v231, 0x3a800000, v199
	v_cmp_gt_f32_e32 vcc, s73, v231
	v_mul_f32_e32 v248, 0x4b800000, v231
	s_nop 0
	v_cndmask_b32_e32 v231, v231, v248, vcc
	v_rsq_f32_e32 v231, v231
	s_nop 0
	v_mul_f32_e32 v248, 0x45800000, v231
	v_cndmask_b32_e32 v231, v231, v248, vcc
	v_mul_f32_e32 v212, v108, v231
	v_mul_f32_e32 v249, v109, v231
	v_mul_f32_e32 v213, v110, v231
	v_mul_f32_e32 v248, v111, v231
	v_max_f32_e32 v212, 0, v212
	v_max_f32_e32 v249, 0, v249
	v_max_f32_e32 v213, 0, v213
	v_max_f32_e32 v248, 0, v248
	v_mul_f32_e32 v212, v212, v212
	v_mul_f32_e32 v249, v249, v249
	v_mul_f32_e32 v213, v213, v213
	v_mul_f32_e32 v248, v248, v248
	v_cvt_pk_bf16_f32 v212, v212, v249
	v_cvt_pk_bf16_f32 v213, v213, v248
	v_mul_f32_e32 v214, v112, v231
	v_mul_f32_e32 v249, v113, v231
	v_mul_f32_e32 v215, v114, v231
	v_mul_f32_e32 v248, v115, v231
	v_max_f32_e32 v214, 0, v214
	v_max_f32_e32 v249, 0, v249
	v_max_f32_e32 v215, 0, v215
	v_max_f32_e32 v248, 0, v248
	v_mul_f32_e32 v214, v214, v214
	v_mul_f32_e32 v249, v249, v249
	v_mul_f32_e32 v215, v215, v215
	v_mul_f32_e32 v248, v248, v248
	v_cvt_pk_bf16_f32 v214, v214, v249
	v_cvt_pk_bf16_f32 v215, v215, v248
	s_add_u32 s30, s92, 0x800
	s_addc_u32 s31, s93, 0
	s_nop 0
	v_permlane16_swap_b32_e32 v212, v214
	v_permlane16_swap_b32_e32 v213, v215
	global_store_dwordx4 v229, v[212:215], s[30:31]
	v_mul_f32_e32 v216, v120, v231
	v_mul_f32_e32 v249, v121, v231
	v_mul_f32_e32 v217, v122, v231
	v_mul_f32_e32 v248, v123, v231
	v_max_f32_e32 v216, 0, v216
	v_max_f32_e32 v249, 0, v249
	v_max_f32_e32 v217, 0, v217
	v_max_f32_e32 v248, 0, v248
	v_mul_f32_e32 v216, v216, v216
	v_mul_f32_e32 v249, v249, v249
	v_mul_f32_e32 v217, v217, v217
	v_mul_f32_e32 v248, v248, v248
	v_cvt_pk_bf16_f32 v216, v216, v249
	v_cvt_pk_bf16_f32 v217, v217, v248
	v_mul_f32_e32 v218, v124, v231
	v_mul_f32_e32 v249, v125, v231
	v_mul_f32_e32 v219, v126, v231
	v_mul_f32_e32 v248, v127, v231
	v_max_f32_e32 v218, 0, v218
	v_max_f32_e32 v249, 0, v249
	v_max_f32_e32 v219, 0, v219
	v_max_f32_e32 v248, 0, v248
	v_mul_f32_e32 v218, v218, v218
	v_mul_f32_e32 v249, v249, v249
	v_mul_f32_e32 v219, v219, v219
	v_mul_f32_e32 v248, v248, v248
	v_cvt_pk_bf16_f32 v218, v218, v249
	v_cvt_pk_bf16_f32 v219, v219, v248
	s_add_u32 s30, s92, 0x200800
	s_addc_u32 s31, s93, 0
	s_nop 0
	v_permlane16_swap_b32_e32 v216, v218
	v_permlane16_swap_b32_e32 v217, v219
	global_store_dwordx4 v229, v[216:219], s[30:31]
	v_mul_f32_e32 v220, v64, v231
	v_mul_f32_e32 v249, v65, v231
	v_mul_f32_e32 v221, v66, v231
	v_mul_f32_e32 v248, v67, v231
	v_max_f32_e32 v220, 0, v220
	v_max_f32_e32 v249, 0, v249
	v_max_f32_e32 v221, 0, v221
	v_max_f32_e32 v248, 0, v248
	v_mul_f32_e32 v220, v220, v220
	v_mul_f32_e32 v249, v249, v249
	v_mul_f32_e32 v221, v221, v221
	v_mul_f32_e32 v248, v248, v248
	v_cvt_pk_bf16_f32 v220, v220, v249
	v_cvt_pk_bf16_f32 v221, v221, v248
	v_mul_f32_e32 v222, v68, v231
	v_mul_f32_e32 v249, v69, v231
	v_mul_f32_e32 v223, v70, v231
	v_mul_f32_e32 v248, v71, v231
	v_max_f32_e32 v222, 0, v222
	v_max_f32_e32 v249, 0, v249
	v_max_f32_e32 v223, 0, v223
	v_max_f32_e32 v248, 0, v248
	v_mul_f32_e32 v222, v222, v222
	v_mul_f32_e32 v249, v249, v249
	v_mul_f32_e32 v223, v223, v223
	v_mul_f32_e32 v248, v248, v248
	v_cvt_pk_bf16_f32 v222, v222, v249
	v_cvt_pk_bf16_f32 v223, v223, v248
	s_add_u32 s30, s92, 0x400800
	s_addc_u32 s31, s93, 0
	s_nop 0
	v_permlane16_swap_b32_e32 v220, v222
	v_permlane16_swap_b32_e32 v221, v223
	global_store_dwordx4 v229, v[220:223], s[30:31]
	v_mul_f32_e32 v224, v80, v231
	v_mul_f32_e32 v249, v81, v231
	v_mul_f32_e32 v225, v82, v231
	v_mul_f32_e32 v248, v83, v231
	v_max_f32_e32 v224, 0, v224
	v_max_f32_e32 v249, 0, v249
	v_max_f32_e32 v225, 0, v225
	v_max_f32_e32 v248, 0, v248
	v_mul_f32_e32 v224, v224, v224
	v_mul_f32_e32 v249, v249, v249
	v_mul_f32_e32 v225, v225, v225
	v_mul_f32_e32 v248, v248, v248
	v_cvt_pk_bf16_f32 v224, v224, v249
	v_cvt_pk_bf16_f32 v225, v225, v248
	v_mul_f32_e32 v226, v56, v231
	v_mul_f32_e32 v249, v57, v231
	v_mul_f32_e32 v227, v58, v231
	v_mul_f32_e32 v248, v59, v231
	v_max_f32_e32 v226, 0, v226
	v_max_f32_e32 v249, 0, v249
	v_max_f32_e32 v227, 0, v227
	v_max_f32_e32 v248, 0, v248
	v_mul_f32_e32 v226, v226, v226
	v_mul_f32_e32 v249, v249, v249
	v_mul_f32_e32 v227, v227, v227
	v_mul_f32_e32 v248, v248, v248
	v_cvt_pk_bf16_f32 v226, v226, v249
	v_cvt_pk_bf16_f32 v227, v227, v248
	s_add_u32 s30, s92, 0x600800
	s_addc_u32 s31, s93, 0
	s_nop 0
	v_permlane16_swap_b32_e32 v224, v226
	v_permlane16_swap_b32_e32 v225, v227
	global_store_dwordx4 v229, v[224:227], s[30:31]
	s_waitcnt vmcnt(12)
	v_add_f32_e32 v231, v186, v187
	v_add_f32_e32 v248, v188, v189
	v_add_f32_e32 v231, v231, v248
	v_add_f32_e32 v249, v190, v191
	v_add_f32_e32 v248, v192, v193
	v_add_f32_e32 v249, v249, v248
	v_add_f32_e32 v231, v231, v249
	v_add_f32_e32 v249, v194, v195
	v_add_f32_e32 v248, v196, v197
	v_add_f32_e32 v249, v249, v248
	v_add_f32_e32 v231, v231, v249
	v_add_f32_e32 v249, v208, v209
	v_add_f32_e32 v248, v210, v211
	v_add_f32_e32 v249, v249, v248
	v_add_f32_e32 v231, v231, v249
	v_fmamk_f32 v231, v231, 0x3a800000, v199
	v_cmp_gt_f32_e32 vcc, s73, v231
	v_mul_f32_e32 v248, 0x4b800000, v231
	s_nop 0
	v_cndmask_b32_e32 v231, v231, v248, vcc
	v_rsq_f32_e32 v231, v231
	s_nop 0
	v_mul_f32_e32 v248, 0x45800000, v231
	v_cndmask_b32_e32 v231, v231, v248, vcc
	v_mul_f32_e32 v212, v132, v231
	v_mul_f32_e32 v249, v133, v231
	v_mul_f32_e32 v213, v134, v231
	v_mul_f32_e32 v248, v135, v231
	v_max_f32_e32 v212, 0, v212
	v_max_f32_e32 v249, 0, v249
	v_max_f32_e32 v213, 0, v213
	v_max_f32_e32 v248, 0, v248
	v_mul_f32_e32 v212, v212, v212
	v_mul_f32_e32 v249, v249, v249
	v_mul_f32_e32 v213, v213, v213
	v_mul_f32_e32 v248, v248, v248
	v_cvt_pk_bf16_f32 v212, v212, v249
	v_cvt_pk_bf16_f32 v213, v213, v248
	v_mul_f32_e32 v214, v136, v231
	v_mul_f32_e32 v249, v137, v231
	v_mul_f32_e32 v215, v138, v231
	v_mul_f32_e32 v248, v139, v231
	v_max_f32_e32 v214, 0, v214
	v_max_f32_e32 v249, 0, v249
	v_max_f32_e32 v215, 0, v215
	v_max_f32_e32 v248, 0, v248
	v_mul_f32_e32 v214, v214, v214
	v_mul_f32_e32 v249, v249, v249
	v_mul_f32_e32 v215, v215, v215
	v_mul_f32_e32 v248, v248, v248
	v_cvt_pk_bf16_f32 v214, v214, v249
	v_cvt_pk_bf16_f32 v215, v215, v248
	s_add_u32 s30, s92, 0xc00
	s_addc_u32 s31, s93, 0
	s_nop 0
	v_permlane16_swap_b32_e32 v212, v214
	v_permlane16_swap_b32_e32 v213, v215
	global_store_dwordx4 v229, v[212:215], s[30:31]
	v_mul_f32_e32 v216, v140, v231
	v_mul_f32_e32 v249, v141, v231
	v_mul_f32_e32 v217, v142, v231
	v_mul_f32_e32 v248, v143, v231
	v_max_f32_e32 v216, 0, v216
	v_max_f32_e32 v249, 0, v249
	v_max_f32_e32 v217, 0, v217
	v_max_f32_e32 v248, 0, v248
	v_mul_f32_e32 v216, v216, v216
	v_mul_f32_e32 v249, v249, v249
	v_mul_f32_e32 v217, v217, v217
	v_mul_f32_e32 v248, v248, v248
	v_cvt_pk_bf16_f32 v216, v216, v249
	v_cvt_pk_bf16_f32 v217, v217, v248
	v_mul_f32_e32 v218, v144, v231
	v_mul_f32_e32 v249, v145, v231
	v_mul_f32_e32 v219, v146, v231
	v_mul_f32_e32 v248, v147, v231
	v_max_f32_e32 v218, 0, v218
	v_max_f32_e32 v249, 0, v249
	v_max_f32_e32 v219, 0, v219
	v_max_f32_e32 v248, 0, v248
	v_mul_f32_e32 v218, v218, v218
	v_mul_f32_e32 v249, v249, v249
	v_mul_f32_e32 v219, v219, v219
	v_mul_f32_e32 v248, v248, v248
	v_cvt_pk_bf16_f32 v218, v218, v249
	v_cvt_pk_bf16_f32 v219, v219, v248
	s_add_u32 s30, s92, 0x200c00
	s_addc_u32 s31, s93, 0
	s_nop 0
	v_permlane16_swap_b32_e32 v216, v218
	v_permlane16_swap_b32_e32 v217, v219
	global_store_dwordx4 v229, v[216:219], s[30:31]
	v_mul_f32_e32 v220, v76, v231
	v_mul_f32_e32 v249, v77, v231
	v_mul_f32_e32 v221, v78, v231
	v_mul_f32_e32 v248, v79, v231
	v_max_f32_e32 v220, 0, v220
	v_max_f32_e32 v249, 0, v249
	v_max_f32_e32 v221, 0, v221
	v_max_f32_e32 v248, 0, v248
	v_mul_f32_e32 v220, v220, v220
	v_mul_f32_e32 v249, v249, v249
	v_mul_f32_e32 v221, v221, v221
	v_mul_f32_e32 v248, v248, v248
	v_cvt_pk_bf16_f32 v220, v220, v249
	v_cvt_pk_bf16_f32 v221, v221, v248
	v_mul_f32_e32 v222, v72, v231
	v_mul_f32_e32 v249, v73, v231
	v_mul_f32_e32 v223, v74, v231
	v_mul_f32_e32 v248, v75, v231
	v_max_f32_e32 v222, 0, v222
	v_max_f32_e32 v249, 0, v249
	v_max_f32_e32 v223, 0, v223
	v_max_f32_e32 v248, 0, v248
	v_mul_f32_e32 v222, v222, v222
	v_mul_f32_e32 v249, v249, v249
	v_mul_f32_e32 v223, v223, v223
	v_mul_f32_e32 v248, v248, v248
	v_cvt_pk_bf16_f32 v222, v222, v249
	v_cvt_pk_bf16_f32 v223, v223, v248
	s_add_u32 s30, s92, 0x400c00
	s_addc_u32 s31, s93, 0
	s_nop 0
	v_permlane16_swap_b32_e32 v220, v222
	v_permlane16_swap_b32_e32 v221, v223
	global_store_dwordx4 v229, v[220:223], s[30:31]
	v_mul_f32_e32 v224, v60, v231
	v_mul_f32_e32 v249, v61, v231
	v_mul_f32_e32 v225, v62, v231
	v_mul_f32_e32 v248, v63, v231
	v_max_f32_e32 v224, 0, v224
	v_max_f32_e32 v249, 0, v249
	v_max_f32_e32 v225, 0, v225
	v_max_f32_e32 v248, 0, v248
	v_mul_f32_e32 v224, v224, v224
	v_mul_f32_e32 v249, v249, v249
	v_mul_f32_e32 v225, v225, v225
	v_mul_f32_e32 v248, v248, v248
	v_cvt_pk_bf16_f32 v224, v224, v249
	v_cvt_pk_bf16_f32 v225, v225, v248
	v_mul_f32_e32 v226, v148, v231
	v_mul_f32_e32 v249, v149, v231
	v_mul_f32_e32 v227, v150, v231
	v_mul_f32_e32 v248, v151, v231
	v_max_f32_e32 v226, 0, v226
	v_max_f32_e32 v249, 0, v249
	v_max_f32_e32 v227, 0, v227
	v_max_f32_e32 v248, 0, v248
	v_mul_f32_e32 v226, v226, v226
	v_mul_f32_e32 v249, v249, v249
	v_mul_f32_e32 v227, v227, v227
	v_mul_f32_e32 v248, v248, v248
	v_cvt_pk_bf16_f32 v226, v226, v249
	v_cvt_pk_bf16_f32 v227, v227, v248
	s_add_u32 s30, s92, 0x600c00
	s_addc_u32 s31, s93, 0
	s_nop 0
	v_permlane16_swap_b32_e32 v224, v226
	v_permlane16_swap_b32_e32 v225, v227
	global_store_dwordx4 v229, v[224:227], s[30:31]
	s_cmp_lg_u32 s23, 0
	s_cbranch_scc0 .LBB0_13

.Lgm1_loop:
	v_add_u32_e32 v248, s30, v155
	v_add_u32_e32 v249, s30, v160
	v_mfma_f32_16x16x32_bf16 v[128:131], v[212:215], v[186:189], v[128:131]
	ds_read_b128 v[0:3], v248
	v_mfma_f32_16x16x32_bf16 v[80:83], v[212:215], v[190:193], v[80:83]
	ds_read_b128 v[16:19], v249 offset:8192
	v_mfma_f32_16x16x32_bf16 v[108:111], v[212:215], v[194:197], v[108:111]
	ds_read_b128 v[4:7], v248 offset:1024
	v_mfma_f32_16x16x32_bf16 v[132:135], v[212:215], v[208:211], v[132:135]
	ds_read_b128 v[20:23], v249 offset:9216
	v_mfma_f32_16x16x32_bf16 v[120:123], v[216:219], v[186:189], v[120:123]
	ds_read_b128 v[8:11], v248 offset:2048
	v_mfma_f32_16x16x32_bf16 v[72:75], v[216:219], v[190:193], v[72:75]
	ds_read_b128 v[162:165], v249 offset:10240
	v_mfma_f32_16x16x32_bf16 v[112:115], v[216:219], v[194:197], v[112:115]
	ds_read_b128 v[12:15], v248 offset:3072
	v_mfma_f32_16x16x32_bf16 v[136:139], v[216:219], v[208:211], v[136:139]
	ds_read_b128 v[166:169], v249 offset:11264
	v_mfma_f32_16x16x32_bf16 v[104:107], v[220:223], v[186:189], v[104:107]
	ds_read_b128 v[170:173], v249 offset:12288
	v_mfma_f32_16x16x32_bf16 v[64:67], v[220:223], v[190:193], v[64:67]
	ds_read_b128 v[174:177], v249 offset:13312
	v_mfma_f32_16x16x32_bf16 v[116:119], v[220:223], v[194:197], v[116:119]
	ds_read_b128 v[178:181], v249 offset:14336
	v_mfma_f32_16x16x32_bf16 v[140:143], v[220:223], v[208:211], v[140:143]
	ds_read_b128 v[182:185], v249 offset:15360
	s_add_u32 m0, s25, s24
	v_mfma_f32_16x16x32_bf16 v[100:103], v[224:227], v[186:189], v[100:103]
	global_load_lds_dwordx4 v244, s[26:27]
	v_mfma_f32_16x16x32_bf16 v[60:63], v[224:227], v[190:193], v[60:63]
	v_mfma_f32_16x16x32_bf16 v[124:127], v[224:227], v[194:197], v[124:127]
	s_add_u32 m0, m0, 0x1000
	v_mfma_f32_16x16x32_bf16 v[144:147], v[224:227], v[208:211], v[144:147]
	global_load_lds_dwordx4 v245, s[26:27]
	v_mfma_f32_16x16x32_bf16 v[68:71], v[228:231], v[186:189], v[68:71]
	v_mfma_f32_16x16x32_bf16 v[36:39], v[228:231], v[190:193], v[36:39]
	s_add_u32 m0, m0, 0x1000
	v_mfma_f32_16x16x32_bf16 v[88:91], v[228:231], v[194:197], v[88:91]
	global_load_lds_dwordx4 v156, s[28:29]
	v_mfma_f32_16x16x32_bf16 v[76:79], v[228:231], v[208:211], v[76:79]
	v_mfma_f32_16x16x32_bf16 v[56:59], v[232:235], v[186:189], v[56:59]
	s_add_u32 m0, m0, 0x1000
	v_mfma_f32_16x16x32_bf16 v[32:35], v[232:235], v[190:193], v[32:35]
	global_load_lds_dwordx4 v157, s[28:29]
	v_mfma_f32_16x16x32_bf16 v[92:95], v[232:235], v[194:197], v[92:95]
	v_mfma_f32_16x16x32_bf16 v[52:55], v[232:235], v[208:211], v[52:55]
	s_add_u32 m0, m0, 0x1000
	v_mfma_f32_16x16x32_bf16 v[48:51], v[236:239], v[186:189], v[48:51]
	global_load_lds_dwordx4 v158, s[28:29]
	v_mfma_f32_16x16x32_bf16 v[28:31], v[236:239], v[190:193], v[28:31]
	v_mfma_f32_16x16x32_bf16 v[96:99], v[236:239], v[194:197], v[96:99]
	s_add_u32 m0, m0, 0x1000
	v_mfma_f32_16x16x32_bf16 v[44:47], v[236:239], v[208:211], v[44:47]
	global_load_lds_dwordx4 v159, s[28:29]
	v_mfma_f32_16x16x32_bf16 v[40:43], v[240:243], v[186:189], v[40:43]
	v_mfma_f32_16x16x32_bf16 v[24:27], v[240:243], v[190:193], v[24:27]
	v_mfma_f32_16x16x32_bf16 v[84:87], v[240:243], v[194:197], v[84:87]
	v_mfma_f32_16x16x32_bf16 v[148:151], v[240:243], v[208:211], v[148:151]
	s_add_u32 s26, s26, 0x40
	s_addc_u32 s27, s27, 0
	s_add_u32 s28, s28, 0x10000
	s_addc_u32 s29, s29, 0
	s_add_u32 s25, s25, 24576
	s_cmp_eq_u32 s25, 73728
	s_cselect_b32 s25, 0, s25
	s_add_u32 s30, s30, 24576
	s_cmp_eq_u32 s30, 73728
	s_cselect_b32 s30, 0, s30
	s_waitcnt vmcnt(6)
	s_waitcnt lgkmcnt(0)
	s_barrier
	v_add_u32_e32 v248, s30, v155
	v_add_u32_e32 v249, s30, v160
	v_mfma_f32_16x16x32_bf16 v[128:131], v[16:19], v[0:3], v[128:131]
	ds_read_b128 v[186:189], v248
	v_mfma_f32_16x16x32_bf16 v[80:83], v[16:19], v[4:7], v[80:83]
	ds_read_b128 v[212:215], v249 offset:8192
	v_mfma_f32_16x16x32_bf16 v[108:111], v[16:19], v[8:11], v[108:111]
	ds_read_b128 v[190:193], v248 offset:1024
	v_mfma_f32_16x16x32_bf16 v[132:135], v[16:19], v[12:15], v[132:135]
	ds_read_b128 v[216:219], v249 offset:9216
	v_mfma_f32_16x16x32_bf16 v[120:123], v[20:23], v[0:3], v[120:123]
	ds_read_b128 v[194:197], v248 offset:2048
	v_mfma_f32_16x16x32_bf16 v[72:75], v[20:23], v[4:7], v[72:75]
	ds_read_b128 v[220:223], v249 offset:10240
	v_mfma_f32_16x16x32_bf16 v[112:115], v[20:23], v[8:11], v[112:115]
	ds_read_b128 v[208:211], v248 offset:3072
	v_mfma_f32_16x16x32_bf16 v[136:139], v[20:23], v[12:15], v[136:139]
	ds_read_b128 v[224:227], v249 offset:11264
	v_mfma_f32_16x16x32_bf16 v[104:107], v[162:165], v[0:3], v[104:107]
	ds_read_b128 v[228:231], v249 offset:12288
	v_mfma_f32_16x16x32_bf16 v[64:67], v[162:165], v[4:7], v[64:67]
	ds_read_b128 v[232:235], v249 offset:13312
	v_mfma_f32_16x16x32_bf16 v[116:119], v[162:165], v[8:11], v[116:119]
	ds_read_b128 v[236:239], v249 offset:14336
	v_mfma_f32_16x16x32_bf16 v[140:143], v[162:165], v[12:15], v[140:143]
	ds_read_b128 v[240:243], v249 offset:15360
	s_add_u32 m0, s25, s24
	v_mfma_f32_16x16x32_bf16 v[100:103], v[166:169], v[0:3], v[100:103]
	global_load_lds_dwordx4 v244, s[26:27]
	v_mfma_f32_16x16x32_bf16 v[60:63], v[166:169], v[4:7], v[60:63]
	v_mfma_f32_16x16x32_bf16 v[124:127], v[166:169], v[8:11], v[124:127]
	s_add_u32 m0, m0, 0x1000
	v_mfma_f32_16x16x32_bf16 v[144:147], v[166:169], v[12:15], v[144:147]
	global_load_lds_dwordx4 v245, s[26:27]
	v_mfma_f32_16x16x32_bf16 v[68:71], v[170:173], v[0:3], v[68:71]
	v_mfma_f32_16x16x32_bf16 v[36:39], v[170:173], v[4:7], v[36:39]
	s_add_u32 m0, m0, 0x1000
	v_mfma_f32_16x16x32_bf16 v[88:91], v[170:173], v[8:11], v[88:91]
	global_load_lds_dwordx4 v156, s[28:29]
	v_mfma_f32_16x16x32_bf16 v[76:79], v[170:173], v[12:15], v[76:79]
	v_mfma_f32_16x16x32_bf16 v[56:59], v[174:177], v[0:3], v[56:59]
	s_add_u32 m0, m0, 0x1000
	v_mfma_f32_16x16x32_bf16 v[32:35], v[174:177], v[4:7], v[32:35]
	global_load_lds_dwordx4 v157, s[28:29]
	v_mfma_f32_16x16x32_bf16 v[92:95], v[174:177], v[8:11], v[92:95]
	v_mfma_f32_16x16x32_bf16 v[52:55], v[174:177], v[12:15], v[52:55]
	s_add_u32 m0, m0, 0x1000
	v_mfma_f32_16x16x32_bf16 v[48:51], v[178:181], v[0:3], v[48:51]
	global_load_lds_dwordx4 v158, s[28:29]
	v_mfma_f32_16x16x32_bf16 v[28:31], v[178:181], v[4:7], v[28:31]
	v_mfma_f32_16x16x32_bf16 v[96:99], v[178:181], v[8:11], v[96:99]
	s_add_u32 m0, m0, 0x1000
	v_mfma_f32_16x16x32_bf16 v[44:47], v[178:181], v[12:15], v[44:47]
	global_load_lds_dwordx4 v159, s[28:29]
	v_mfma_f32_16x16x32_bf16 v[40:43], v[182:185], v[0:3], v[40:43]
	v_mfma_f32_16x16x32_bf16 v[24:27], v[182:185], v[4:7], v[24:27]
	v_mfma_f32_16x16x32_bf16 v[84:87], v[182:185], v[8:11], v[84:87]
	v_mfma_f32_16x16x32_bf16 v[148:151], v[182:185], v[12:15], v[148:151]
	s_add_u32 s26, s26, 0x40
	s_addc_u32 s27, s27, 0
	s_add_u32 s28, s28, 0x10000
	s_addc_u32 s29, s29, 0
	s_add_u32 s25, s25, 24576
	s_cmp_eq_u32 s25, 73728
	s_cselect_b32 s25, 0, s25
	s_add_u32 s30, s30, 24576
	s_cmp_eq_u32 s30, 73728
	s_cselect_b32 s30, 0, s30
	s_waitcnt vmcnt(6)
	s_waitcnt lgkmcnt(0)
	s_barrier
	s_sub_u32 s31, s31, 1
	s_cmp_lg_u32 s31, 0
	s_cbranch_scc1 .Lgm1_loop
	v_add_u32_e32 v248, s30, v155
	v_add_u32_e32 v249, s30, v160
	v_mfma_f32_16x16x32_bf16 v[128:131], v[212:215], v[186:189], v[128:131]
	ds_read_b128 v[0:3], v248
	v_mfma_f32_16x16x32_bf16 v[80:83], v[212:215], v[190:193], v[80:83]
	ds_read_b128 v[16:19], v249 offset:8192
	v_mfma_f32_16x16x32_bf16 v[108:111], v[212:215], v[194:197], v[108:111]
	ds_read_b128 v[4:7], v248 offset:1024
	v_mfma_f32_16x16x32_bf16 v[132:135], v[212:215], v[208:211], v[132:135]
	ds_read_b128 v[20:23], v249 offset:9216
	v_mfma_f32_16x16x32_bf16 v[120:123], v[216:219], v[186:189], v[120:123]
	ds_read_b128 v[8:11], v248 offset:2048
	v_mfma_f32_16x16x32_bf16 v[72:75], v[216:219], v[190:193], v[72:75]
	ds_read_b128 v[162:165], v249 offset:10240
	v_mfma_f32_16x16x32_bf16 v[112:115], v[216:219], v[194:197], v[112:115]
	ds_read_b128 v[12:15], v248 offset:3072
	v_mfma_f32_16x16x32_bf16 v[136:139], v[216:219], v[208:211], v[136:139]
	ds_read_b128 v[166:169], v249 offset:11264
	v_mfma_f32_16x16x32_bf16 v[104:107], v[220:223], v[186:189], v[104:107]
	ds_read_b128 v[170:173], v249 offset:12288
	v_mfma_f32_16x16x32_bf16 v[64:67], v[220:223], v[190:193], v[64:67]
	ds_read_b128 v[174:177], v249 offset:13312
	v_mfma_f32_16x16x32_bf16 v[116:119], v[220:223], v[194:197], v[116:119]
	ds_read_b128 v[178:181], v249 offset:14336
	v_mfma_f32_16x16x32_bf16 v[140:143], v[220:223], v[208:211], v[140:143]
	ds_read_b128 v[182:185], v249 offset:15360
	s_add_u32 m0, s25, s24
	v_mfma_f32_16x16x32_bf16 v[100:103], v[224:227], v[186:189], v[100:103]
	global_load_lds_dwordx4 v244, s[26:27]
	v_mfma_f32_16x16x32_bf16 v[60:63], v[224:227], v[190:193], v[60:63]
	v_mfma_f32_16x16x32_bf16 v[124:127], v[224:227], v[194:197], v[124:127]
	s_add_u32 m0, m0, 0x1000
	v_mfma_f32_16x16x32_bf16 v[144:147], v[224:227], v[208:211], v[144:147]
	global_load_lds_dwordx4 v245, s[26:27]
	v_mfma_f32_16x16x32_bf16 v[68:71], v[228:231], v[186:189], v[68:71]
	v_mfma_f32_16x16x32_bf16 v[36:39], v[228:231], v[190:193], v[36:39]
	s_add_u32 m0, m0, 0x1000
	v_mfma_f32_16x16x32_bf16 v[88:91], v[228:231], v[194:197], v[88:91]
	global_load_lds_dwordx4 v156, s[28:29]
	v_mfma_f32_16x16x32_bf16 v[76:79], v[228:231], v[208:211], v[76:79]
	v_mfma_f32_16x16x32_bf16 v[56:59], v[232:235], v[186:189], v[56:59]
	s_add_u32 m0, m0, 0x1000
	v_mfma_f32_16x16x32_bf16 v[32:35], v[232:235], v[190:193], v[32:35]
	global_load_lds_dwordx4 v157, s[28:29]
	v_mfma_f32_16x16x32_bf16 v[92:95], v[232:235], v[194:197], v[92:95]
	v_mfma_f32_16x16x32_bf16 v[52:55], v[232:235], v[208:211], v[52:55]
	s_add_u32 m0, m0, 0x1000
	v_mfma_f32_16x16x32_bf16 v[48:51], v[236:239], v[186:189], v[48:51]
	global_load_lds_dwordx4 v158, s[28:29]
	v_mfma_f32_16x16x32_bf16 v[28:31], v[236:239], v[190:193], v[28:31]
	v_mfma_f32_16x16x32_bf16 v[96:99], v[236:239], v[194:197], v[96:99]
	s_add_u32 m0, m0, 0x1000
	v_mfma_f32_16x16x32_bf16 v[44:47], v[236:239], v[208:211], v[44:47]
	global_load_lds_dwordx4 v159, s[28:29]
	v_mfma_f32_16x16x32_bf16 v[40:43], v[240:243], v[186:189], v[40:43]
	v_mfma_f32_16x16x32_bf16 v[24:27], v[240:243], v[190:193], v[24:27]
	v_mfma_f32_16x16x32_bf16 v[84:87], v[240:243], v[194:197], v[84:87]
	v_mfma_f32_16x16x32_bf16 v[148:151], v[240:243], v[208:211], v[148:151]
	s_add_u32 s26, s26, 0x40
	s_addc_u32 s27, s27, 0
	s_add_u32 s28, s28, 0x10000
	s_addc_u32 s29, s29, 0
	s_add_u32 s25, s25, 24576
	s_cmp_eq_u32 s25, 73728
	s_cselect_b32 s25, 0, s25
	s_add_u32 s30, s30, 24576
	s_cmp_eq_u32 s30, 73728
	s_cselect_b32 s30, 0, s30
	s_waitcnt vmcnt(6)
	s_waitcnt lgkmcnt(0)
	s_barrier
	v_add_u32_e32 v248, s30, v155
	v_add_u32_e32 v249, s30, v160
	v_mfma_f32_16x16x32_bf16 v[128:131], v[16:19], v[0:3], v[128:131]
	ds_read_b128 v[186:189], v248
	v_mfma_f32_16x16x32_bf16 v[80:83], v[16:19], v[4:7], v[80:83]
	ds_read_b128 v[212:215], v249 offset:8192
	v_mfma_f32_16x16x32_bf16 v[108:111], v[16:19], v[8:11], v[108:111]
	ds_read_b128 v[190:193], v248 offset:1024
	v_mfma_f32_16x16x32_bf16 v[132:135], v[16:19], v[12:15], v[132:135]
	ds_read_b128 v[216:219], v249 offset:9216
	v_mfma_f32_16x16x32_bf16 v[120:123], v[20:23], v[0:3], v[120:123]
	ds_read_b128 v[194:197], v248 offset:2048
	v_mfma_f32_16x16x32_bf16 v[72:75], v[20:23], v[4:7], v[72:75]
	ds_read_b128 v[220:223], v249 offset:10240
	v_mfma_f32_16x16x32_bf16 v[112:115], v[20:23], v[8:11], v[112:115]
	ds_read_b128 v[208:211], v248 offset:3072
	v_mfma_f32_16x16x32_bf16 v[136:139], v[20:23], v[12:15], v[136:139]
	ds_read_b128 v[224:227], v249 offset:11264
	v_mfma_f32_16x16x32_bf16 v[104:107], v[162:165], v[0:3], v[104:107]
	ds_read_b128 v[228:231], v249 offset:12288
	v_mfma_f32_16x16x32_bf16 v[64:67], v[162:165], v[4:7], v[64:67]
	ds_read_b128 v[232:235], v249 offset:13312
	v_mfma_f32_16x16x32_bf16 v[116:119], v[162:165], v[8:11], v[116:119]
	ds_read_b128 v[236:239], v249 offset:14336
	v_mfma_f32_16x16x32_bf16 v[140:143], v[162:165], v[12:15], v[140:143]
	ds_read_b128 v[240:243], v249 offset:15360
	v_mfma_f32_16x16x32_bf16 v[100:103], v[166:169], v[0:3], v[100:103]
	v_mfma_f32_16x16x32_bf16 v[60:63], v[166:169], v[4:7], v[60:63]
	v_mfma_f32_16x16x32_bf16 v[124:127], v[166:169], v[8:11], v[124:127]
	v_mfma_f32_16x16x32_bf16 v[144:147], v[166:169], v[12:15], v[144:147]
	v_mfma_f32_16x16x32_bf16 v[68:71], v[170:173], v[0:3], v[68:71]
	v_mfma_f32_16x16x32_bf16 v[36:39], v[170:173], v[4:7], v[36:39]
	v_mfma_f32_16x16x32_bf16 v[88:91], v[170:173], v[8:11], v[88:91]
	v_mfma_f32_16x16x32_bf16 v[76:79], v[170:173], v[12:15], v[76:79]
	v_mfma_f32_16x16x32_bf16 v[56:59], v[174:177], v[0:3], v[56:59]
	v_mfma_f32_16x16x32_bf16 v[32:35], v[174:177], v[4:7], v[32:35]
	v_mfma_f32_16x16x32_bf16 v[92:95], v[174:177], v[8:11], v[92:95]
	v_mfma_f32_16x16x32_bf16 v[52:55], v[174:177], v[12:15], v[52:55]
	v_mfma_f32_16x16x32_bf16 v[48:51], v[178:181], v[0:3], v[48:51]
	v_mfma_f32_16x16x32_bf16 v[28:31], v[178:181], v[4:7], v[28:31]
	v_mfma_f32_16x16x32_bf16 v[96:99], v[178:181], v[8:11], v[96:99]
	v_mfma_f32_16x16x32_bf16 v[44:47], v[178:181], v[12:15], v[44:47]
	v_mfma_f32_16x16x32_bf16 v[40:43], v[182:185], v[0:3], v[40:43]
	v_mfma_f32_16x16x32_bf16 v[24:27], v[182:185], v[4:7], v[24:27]
	v_mfma_f32_16x16x32_bf16 v[84:87], v[182:185], v[8:11], v[84:87]
	v_mfma_f32_16x16x32_bf16 v[148:151], v[182:185], v[12:15], v[148:151]
	s_add_u32 s30, s30, 24576
	s_cmp_eq_u32 s30, 73728
	s_cselect_b32 s30, 0, s30
	s_waitcnt vmcnt(0)
	s_waitcnt lgkmcnt(0)
	s_barrier
	v_add_u32_e32 v248, s30, v155
	v_add_u32_e32 v249, s30, v160
	v_mfma_f32_16x16x32_bf16 v[128:131], v[212:215], v[186:189], v[128:131]
	ds_read_b128 v[0:3], v248
	v_mfma_f32_16x16x32_bf16 v[80:83], v[212:215], v[190:193], v[80:83]
	ds_read_b128 v[16:19], v249 offset:8192
	v_mfma_f32_16x16x32_bf16 v[108:111], v[212:215], v[194:197], v[108:111]
	ds_read_b128 v[4:7], v248 offset:1024
	v_mfma_f32_16x16x32_bf16 v[132:135], v[212:215], v[208:211], v[132:135]
	ds_read_b128 v[20:23], v249 offset:9216
	v_mfma_f32_16x16x32_bf16 v[120:123], v[216:219], v[186:189], v[120:123]
	ds_read_b128 v[8:11], v248 offset:2048
	v_mfma_f32_16x16x32_bf16 v[72:75], v[216:219], v[190:193], v[72:75]
	ds_read_b128 v[162:165], v249 offset:10240
	v_mfma_f32_16x16x32_bf16 v[112:115], v[216:219], v[194:197], v[112:115]
	ds_read_b128 v[12:15], v248 offset:3072
	v_mfma_f32_16x16x32_bf16 v[136:139], v[216:219], v[208:211], v[136:139]
	ds_read_b128 v[166:169], v249 offset:11264
	v_mfma_f32_16x16x32_bf16 v[104:107], v[220:223], v[186:189], v[104:107]
	ds_read_b128 v[170:173], v249 offset:12288
	v_mfma_f32_16x16x32_bf16 v[64:67], v[220:223], v[190:193], v[64:67]
	ds_read_b128 v[174:177], v249 offset:13312
	v_mfma_f32_16x16x32_bf16 v[116:119], v[220:223], v[194:197], v[116:119]
	ds_read_b128 v[178:181], v249 offset:14336
	v_mfma_f32_16x16x32_bf16 v[140:143], v[220:223], v[208:211], v[140:143]
	ds_read_b128 v[182:185], v249 offset:15360
	v_mfma_f32_16x16x32_bf16 v[100:103], v[224:227], v[186:189], v[100:103]
	v_mfma_f32_16x16x32_bf16 v[60:63], v[224:227], v[190:193], v[60:63]
	v_mfma_f32_16x16x32_bf16 v[124:127], v[224:227], v[194:197], v[124:127]
	v_mfma_f32_16x16x32_bf16 v[144:147], v[224:227], v[208:211], v[144:147]
	v_mfma_f32_16x16x32_bf16 v[68:71], v[228:231], v[186:189], v[68:71]
	v_mfma_f32_16x16x32_bf16 v[36:39], v[228:231], v[190:193], v[36:39]
	v_mfma_f32_16x16x32_bf16 v[88:91], v[228:231], v[194:197], v[88:91]
	v_mfma_f32_16x16x32_bf16 v[76:79], v[228:231], v[208:211], v[76:79]
	v_mfma_f32_16x16x32_bf16 v[56:59], v[232:235], v[186:189], v[56:59]
	v_mfma_f32_16x16x32_bf16 v[32:35], v[232:235], v[190:193], v[32:35]
	v_mfma_f32_16x16x32_bf16 v[92:95], v[232:235], v[194:197], v[92:95]
	v_mfma_f32_16x16x32_bf16 v[52:55], v[232:235], v[208:211], v[52:55]
	v_mfma_f32_16x16x32_bf16 v[48:51], v[236:239], v[186:189], v[48:51]
	v_mfma_f32_16x16x32_bf16 v[28:31], v[236:239], v[190:193], v[28:31]
	v_mfma_f32_16x16x32_bf16 v[96:99], v[236:239], v[194:197], v[96:99]
	v_mfma_f32_16x16x32_bf16 v[44:47], v[236:239], v[208:211], v[44:47]
	v_mfma_f32_16x16x32_bf16 v[40:43], v[240:243], v[186:189], v[40:43]
	v_mfma_f32_16x16x32_bf16 v[24:27], v[240:243], v[190:193], v[24:27]
	v_mfma_f32_16x16x32_bf16 v[84:87], v[240:243], v[194:197], v[84:87]
	v_mfma_f32_16x16x32_bf16 v[148:151], v[240:243], v[208:211], v[148:151]
	s_add_u32 s30, s30, 24576
	s_cmp_eq_u32 s30, 73728
	s_cselect_b32 s30, 0, s30
	s_waitcnt lgkmcnt(0)
	s_barrier
	v_mfma_f32_16x16x32_bf16 v[128:131], v[16:19], v[0:3], v[128:131]
	v_mfma_f32_16x16x32_bf16 v[80:83], v[16:19], v[4:7], v[80:83]
	v_mfma_f32_16x16x32_bf16 v[108:111], v[16:19], v[8:11], v[108:111]
	v_mfma_f32_16x16x32_bf16 v[132:135], v[16:19], v[12:15], v[132:135]
	v_mfma_f32_16x16x32_bf16 v[120:123], v[20:23], v[0:3], v[120:123]
	v_mfma_f32_16x16x32_bf16 v[72:75], v[20:23], v[4:7], v[72:75]
	v_mfma_f32_16x16x32_bf16 v[112:115], v[20:23], v[8:11], v[112:115]
	v_mfma_f32_16x16x32_bf16 v[136:139], v[20:23], v[12:15], v[136:139]
	v_mfma_f32_16x16x32_bf16 v[104:107], v[162:165], v[0:3], v[104:107]
	v_mfma_f32_16x16x32_bf16 v[64:67], v[162:165], v[4:7], v[64:67]
	v_mfma_f32_16x16x32_bf16 v[116:119], v[162:165], v[8:11], v[116:119]
	v_mfma_f32_16x16x32_bf16 v[140:143], v[162:165], v[12:15], v[140:143]
	v_mfma_f32_16x16x32_bf16 v[100:103], v[166:169], v[0:3], v[100:103]
	v_mfma_f32_16x16x32_bf16 v[60:63], v[166:169], v[4:7], v[60:63]
	v_mfma_f32_16x16x32_bf16 v[124:127], v[166:169], v[8:11], v[124:127]
	v_mfma_f32_16x16x32_bf16 v[144:147], v[166:169], v[12:15], v[144:147]
	v_mfma_f32_16x16x32_bf16 v[68:71], v[170:173], v[0:3], v[68:71]
	v_mfma_f32_16x16x32_bf16 v[36:39], v[170:173], v[4:7], v[36:39]
	v_mfma_f32_16x16x32_bf16 v[88:91], v[170:173], v[8:11], v[88:91]
	v_mfma_f32_16x16x32_bf16 v[76:79], v[170:173], v[12:15], v[76:79]
	v_mfma_f32_16x16x32_bf16 v[56:59], v[174:177], v[0:3], v[56:59]
	v_mfma_f32_16x16x32_bf16 v[32:35], v[174:177], v[4:7], v[32:35]
	v_mfma_f32_16x16x32_bf16 v[92:95], v[174:177], v[8:11], v[92:95]
	v_mfma_f32_16x16x32_bf16 v[52:55], v[174:177], v[12:15], v[52:55]
	v_mfma_f32_16x16x32_bf16 v[48:51], v[178:181], v[0:3], v[48:51]
	v_mfma_f32_16x16x32_bf16 v[28:31], v[178:181], v[4:7], v[28:31]
	v_mfma_f32_16x16x32_bf16 v[96:99], v[178:181], v[8:11], v[96:99]
	v_mfma_f32_16x16x32_bf16 v[44:47], v[178:181], v[12:15], v[44:47]
	v_mfma_f32_16x16x32_bf16 v[40:43], v[182:185], v[0:3], v[40:43]
	v_mfma_f32_16x16x32_bf16 v[24:27], v[182:185], v[4:7], v[24:27]
	v_mfma_f32_16x16x32_bf16 v[84:87], v[182:185], v[8:11], v[84:87]
	v_mfma_f32_16x16x32_bf16 v[148:151], v[182:185], v[12:15], v[148:151]
	v_mov_b32 v250, v198
	s_nop 0
	v_and_b32_e32 v251, 15, v250
	v_bfe_u32 v156, v250, 4, 2
	v_bfe_u32 v157, v250, 6, 1
	v_bfe_u32 v158, v250, 7, 1
	v_lshl_add_u32 v158, v158, 6, s10
	v_add_u32_e32 v158, v158, v251
	v_lshl_add_u32 v157, v157, 7, s11
	v_lshl_add_u32 v159, v156, 2, v157
	v_lshlrev_b32_e32 v246, 2, v159
	v_lshl_add_u32 v244, v158, 12, v246
	v_lshlrev_b32_e32 v161, 1, v159
	v_lshl_add_u32 v245, v158, 11, v161
	v_and_b32_e32 v254, 1, v156
	v_mul_u32_u24_e32 v254, 24, v254
	v_lshl_add_u32 v254, v156, 3, v254
	v_lshl_add_u32 v254, v158, 6, v254
	v_lshrrev_b32_e32 v161, 5, v157
	v_lshl_add_u32 v254, v161, 21, v254
	v_lshrrev_b32_e32 v161, 6, v157
	v_lshlrev_b32_e32 v161, 2, v161
	v_lshl_add_u32 v247, v158, 6, v161
	v_xor_b32_e32 v248, 16, v200
	v_lshlrev_b32_e32 v248, 2, v248
	v_xor_b32_e32 v249, 32, v200
	v_lshlrev_b32_e32 v249, 2, v249
	s_mov_b32 s24, s6
	s_mov_b32 s25, s7
	s_mov_b32 s26, s78
	s_mov_b32 s27, s79
	v_readlane_b32 s28, v253, 21
	v_readlane_b32 s29, v253, 22
	s_mov_b32 s30, s94
	s_mov_b32 s31, s95
	s_mov_b32 s22, s28
	s_mov_b32 s23, s29
	global_load_dwordx4 v[208:211], v246, s[8:9]
	global_load_dwordx4 v[212:215], v246, s[8:9] offset:64
	global_load_dwordx4 v[216:219], v246, s[8:9] offset:128
	global_load_dwordx4 v[220:223], v246, s[8:9] offset:192
	global_load_dwordx4 v[224:227], v246, s[8:9] offset:256
	global_load_dwordx4 v[228:231], v246, s[8:9] offset:320
	global_load_dwordx4 v[232:235], v246, s[8:9] offset:384
	global_load_dwordx4 v[236:239], v246, s[8:9] offset:448
	global_load_dwordx4 v[0:3], v244, s[24:25]
	global_load_dwordx4 v[4:7], v244, s[24:25] offset:64
	global_load_dwordx4 v[8:11], v244, s[24:25] offset:128
	global_load_dwordx4 v[12:15], v244, s[24:25] offset:192
	global_load_dwordx4 v[16:19], v244, s[24:25] offset:256
	global_load_dwordx4 v[20:23], v244, s[24:25] offset:320
	global_load_dwordx4 v[162:165], v244, s[24:25] offset:384
	global_load_dwordx4 v[166:169], v244, s[24:25] offset:448
	s_add_u32 s24, s24, 0x10000
	s_addc_u32 s25, s25, 0
	global_load_dwordx4 v[170:173], v244, s[24:25]
	global_load_dwordx4 v[174:177], v244, s[24:25] offset:64
	global_load_dwordx4 v[178:181], v244, s[24:25] offset:128
	global_load_dwordx4 v[182:185], v244, s[24:25] offset:192
	global_load_dwordx4 v[186:189], v244, s[24:25] offset:256
	global_load_dwordx4 v[190:193], v244, s[24:25] offset:320
	global_load_dwordx4 v[194:197], v244, s[24:25] offset:384
	global_load_dwordx4 v[240:243], v244, s[24:25] offset:448
	s_add_u32 s24, s24, 0x10000
	s_addc_u32 s25, s25, 0
	s_waitcnt vmcnt(12)
	v_add_f32_e32 v0, v128, v0
	v_add_f32_e32 v1, v129, v1
	v_add_f32_e32 v2, v130, v2
	v_add_f32_e32 v3, v131, v3
	global_store_dwordx4 v244, v[0:3], s[26:27]
	v_mul_f32_e32 v158, v0, v0
	v_mul_f32_e32 v159, v1, v1
	v_mul_f32_e32 v250, v2, v2
	v_mul_f32_e32 v251, v3, v3
	v_add_f32_e32 v158, v158, v159
	v_add_f32_e32 v250, v250, v251
	v_add_f32_e32 v161, v158, v250
	v_mul_f32_e32 v156, v0, v208
	v_mul_f32_e32 v157, v1, v209
	v_mul_f32_e32 v158, v2, v210
	v_mul_f32_e32 v159, v3, v211
	v_cvt_pk_bf16_f32 v156, v156, v157
	v_cvt_pk_bf16_f32 v157, v158, v159
	v_add_f32_e32 v4, v120, v4
	v_add_f32_e32 v5, v121, v5
	v_add_f32_e32 v6, v122, v6
	v_add_f32_e32 v7, v123, v7
	global_store_dwordx4 v244, v[4:7], s[26:27] offset:64
	v_mul_f32_e32 v158, v4, v4
	v_mul_f32_e32 v159, v5, v5
	v_mul_f32_e32 v250, v6, v6
	v_mul_f32_e32 v251, v7, v7
	v_add_f32_e32 v158, v158, v159
	v_add_f32_e32 v250, v250, v251
	v_add_f32_e32 v158, v158, v250
	v_add_f32_e32 v161, v161, v158
	v_mul_f32_e32 v158, v4, v212
	v_mul_f32_e32 v159, v5, v213
	v_mul_f32_e32 v250, v6, v214
	v_mul_f32_e32 v251, v7, v215
	v_cvt_pk_bf16_f32 v158, v158, v159
	v_cvt_pk_bf16_f32 v159, v250, v251
	s_nop 1
	v_permlane16_swap_b32_e32 v156, v158
	v_permlane16_swap_b32_e32 v157, v159
	s_add_u32 s28, s22, 0x0
	s_addc_u32 s29, s23, 0
	global_store_dwordx4 v254, v[156:159], s[28:29]
	v_add_f32_e32 v8, v104, v8
	v_add_f32_e32 v9, v105, v9
	v_add_f32_e32 v10, v106, v10
	v_add_f32_e32 v11, v107, v11
	global_store_dwordx4 v244, v[8:11], s[26:27] offset:128
	v_mul_f32_e32 v158, v8, v8
	v_mul_f32_e32 v159, v9, v9
	v_mul_f32_e32 v250, v10, v10
	v_mul_f32_e32 v251, v11, v11
	v_add_f32_e32 v158, v158, v159
	v_add_f32_e32 v250, v250, v251
	v_add_f32_e32 v158, v158, v250
	v_add_f32_e32 v161, v161, v158
	v_mul_f32_e32 v156, v8, v216
	v_mul_f32_e32 v157, v9, v217
	v_mul_f32_e32 v158, v10, v218
	v_mul_f32_e32 v159, v11, v219
	v_cvt_pk_bf16_f32 v156, v156, v157
	v_cvt_pk_bf16_f32 v157, v158, v159
	v_add_f32_e32 v12, v100, v12
	v_add_f32_e32 v13, v101, v13
	v_add_f32_e32 v14, v102, v14
	v_add_f32_e32 v15, v103, v15
	global_store_dwordx4 v244, v[12:15], s[26:27] offset:192
	v_mul_f32_e32 v158, v12, v12
	v_mul_f32_e32 v159, v13, v13
	v_mul_f32_e32 v250, v14, v14
	v_mul_f32_e32 v251, v15, v15
	v_add_f32_e32 v158, v158, v159
	v_add_f32_e32 v250, v250, v251
	v_add_f32_e32 v158, v158, v250
	v_add_f32_e32 v161, v161, v158
	v_mul_f32_e32 v158, v12, v220
	v_mul_f32_e32 v159, v13, v221
	v_mul_f32_e32 v250, v14, v222
	v_mul_f32_e32 v251, v15, v223
	v_cvt_pk_bf16_f32 v158, v158, v159
	v_cvt_pk_bf16_f32 v159, v250, v251
	s_nop 1
	v_permlane16_swap_b32_e32 v156, v158
	v_permlane16_swap_b32_e32 v157, v159
	s_add_u32 s28, s22, 0x200000
	s_addc_u32 s29, s23, 0
	global_store_dwordx4 v254, v[156:159], s[28:29]
	ds_bpermute_b32 v158, v248, v161
	s_waitcnt lgkmcnt(0)
	v_add_f32_e32 v161, v161, v158
	ds_bpermute_b32 v158, v249, v161
	s_waitcnt lgkmcnt(0)
	v_add_f32_e32 v161, v161, v158
	global_store_dword v247, v161, s[30:31]
	global_load_dwordx4 v[0:3], v244, s[24:25]
	global_load_dwordx4 v[4:7], v244, s[24:25] offset:64
	global_load_dwordx4 v[8:11], v244, s[24:25] offset:128
	global_load_dwordx4 v[12:15], v244, s[24:25] offset:192
	s_waitcnt vmcnt(19)
	v_add_f32_e32 v16, v68, v16
	v_add_f32_e32 v17, v69, v17
	v_add_f32_e32 v18, v70, v18
	v_add_f32_e32 v19, v71, v19
	global_store_dwordx4 v244, v[16:19], s[26:27] offset:256
	v_mul_f32_e32 v158, v16, v16
	v_mul_f32_e32 v159, v17, v17
	v_mul_f32_e32 v250, v18, v18
	v_mul_f32_e32 v251, v19, v19
	v_add_f32_e32 v158, v158, v159
	v_add_f32_e32 v250, v250, v251
	v_add_f32_e32 v161, v158, v250
	v_mul_f32_e32 v156, v16, v224
	v_mul_f32_e32 v157, v17, v225
	v_mul_f32_e32 v158, v18, v226
	v_mul_f32_e32 v159, v19, v227
	v_cvt_pk_bf16_f32 v156, v156, v157
	v_cvt_pk_bf16_f32 v157, v158, v159
	v_add_f32_e32 v20, v56, v20
	v_add_f32_e32 v21, v57, v21
	v_add_f32_e32 v22, v58, v22
	v_add_f32_e32 v23, v59, v23
	global_store_dwordx4 v244, v[20:23], s[26:27] offset:320
	v_mul_f32_e32 v158, v20, v20
	v_mul_f32_e32 v159, v21, v21
	v_mul_f32_e32 v250, v22, v22
	v_mul_f32_e32 v251, v23, v23
	v_add_f32_e32 v158, v158, v159
	v_add_f32_e32 v250, v250, v251
	v_add_f32_e32 v158, v158, v250
	v_add_f32_e32 v161, v161, v158
	v_mul_f32_e32 v158, v20, v228
	v_mul_f32_e32 v159, v21, v229
	v_mul_f32_e32 v250, v22, v230
	v_mul_f32_e32 v251, v23, v231
	v_cvt_pk_bf16_f32 v158, v158, v159
	v_cvt_pk_bf16_f32 v159, v250, v251
	s_nop 1
	v_permlane16_swap_b32_e32 v156, v158
	v_permlane16_swap_b32_e32 v157, v159
	s_add_u32 s28, s22, 0x400000
	s_addc_u32 s29, s23, 0
	global_store_dwordx4 v254, v[156:159], s[28:29]
	v_add_f32_e32 v162, v48, v162
	v_add_f32_e32 v163, v49, v163
	v_add_f32_e32 v164, v50, v164
	v_add_f32_e32 v165, v51, v165
	global_store_dwordx4 v244, v[162:165], s[26:27] offset:384
	v_mul_f32_e32 v158, v162, v162
	v_mul_f32_e32 v159, v163, v163
	v_mul_f32_e32 v250, v164, v164
	v_mul_f32_e32 v251, v165, v165
	v_add_f32_e32 v158, v158, v159
	v_add_f32_e32 v250, v250, v251
	v_add_f32_e32 v158, v158, v250
	v_add_f32_e32 v161, v161, v158
	v_mul_f32_e32 v156, v162, v232
	v_mul_f32_e32 v157, v163, v233
	v_mul_f32_e32 v158, v164, v234
	v_mul_f32_e32 v159, v165, v235
	v_cvt_pk_bf16_f32 v156, v156, v157
	v_cvt_pk_bf16_f32 v157, v158, v159
	v_add_f32_e32 v166, v40, v166
	v_add_f32_e32 v167, v41, v167
	v_add_f32_e32 v168, v42, v168
	v_add_f32_e32 v169, v43, v169
	global_store_dwordx4 v244, v[166:169], s[26:27] offset:448
	v_mul_f32_e32 v158, v166, v166
	v_mul_f32_e32 v159, v167, v167
	v_mul_f32_e32 v250, v168, v168
	v_mul_f32_e32 v251, v169, v169
	v_add_f32_e32 v158, v158, v159
	v_add_f32_e32 v250, v250, v251
	v_add_f32_e32 v158, v158, v250
	v_add_f32_e32 v161, v161, v158
	v_mul_f32_e32 v158, v166, v236
	v_mul_f32_e32 v159, v167, v237
	v_mul_f32_e32 v250, v168, v238
	v_mul_f32_e32 v251, v169, v239
	v_cvt_pk_bf16_f32 v158, v158, v159
	v_cvt_pk_bf16_f32 v159, v250, v251
	s_nop 1
	v_permlane16_swap_b32_e32 v156, v158
	v_permlane16_swap_b32_e32 v157, v159
	s_add_u32 s28, s22, 0x600000
	s_addc_u32 s29, s23, 0
	global_store_dwordx4 v254, v[156:159], s[28:29]
	ds_bpermute_b32 v158, v248, v161
	s_waitcnt lgkmcnt(0)
	v_add_f32_e32 v161, v161, v158
	ds_bpermute_b32 v158, v249, v161
	s_waitcnt lgkmcnt(0)
	v_add_f32_e32 v161, v161, v158
	global_store_dword v247, v161, s[30:31] offset:4
	s_add_u32 s26, s26, 0x10000
	s_addc_u32 s27, s27, 0
	s_add_u32 s30, s30, 0x400
	s_addc_u32 s31, s31, 0
	global_load_dwordx4 v[16:19], v244, s[24:25] offset:256
	global_load_dwordx4 v[20:23], v244, s[24:25] offset:320
	global_load_dwordx4 v[162:165], v244, s[24:25] offset:384
	global_load_dwordx4 v[166:169], v244, s[24:25] offset:448
	s_add_u32 s24, s24, 0x10000
	s_addc_u32 s25, s25, 0
	s_waitcnt vmcnt(26)
	v_add_f32_e32 v170, v80, v170
	v_add_f32_e32 v171, v81, v171
	v_add_f32_e32 v172, v82, v172
	v_add_f32_e32 v173, v83, v173
	global_store_dwordx4 v244, v[170:173], s[26:27]
	v_mul_f32_e32 v158, v170, v170
	v_mul_f32_e32 v159, v171, v171
	v_mul_f32_e32 v250, v172, v172
	v_mul_f32_e32 v251, v173, v173
	v_add_f32_e32 v158, v158, v159
	v_add_f32_e32 v250, v250, v251
	v_add_f32_e32 v161, v158, v250
	v_mul_f32_e32 v156, v170, v208
	v_mul_f32_e32 v157, v171, v209
	v_mul_f32_e32 v158, v172, v210
	v_mul_f32_e32 v159, v173, v211
	v_cvt_pk_bf16_f32 v156, v156, v157
	v_cvt_pk_bf16_f32 v157, v158, v159
	v_add_f32_e32 v174, v72, v174
	v_add_f32_e32 v175, v73, v175
	v_add_f32_e32 v176, v74, v176
	v_add_f32_e32 v177, v75, v177
	global_store_dwordx4 v244, v[174:177], s[26:27] offset:64
	v_mul_f32_e32 v158, v174, v174
	v_mul_f32_e32 v159, v175, v175
	v_mul_f32_e32 v250, v176, v176
	v_mul_f32_e32 v251, v177, v177
	v_add_f32_e32 v158, v158, v159
	v_add_f32_e32 v250, v250, v251
	v_add_f32_e32 v158, v158, v250
	v_add_f32_e32 v161, v161, v158
	v_mul_f32_e32 v158, v174, v212
	v_mul_f32_e32 v159, v175, v213
	v_mul_f32_e32 v250, v176, v214
	v_mul_f32_e32 v251, v177, v215
	v_cvt_pk_bf16_f32 v158, v158, v159
	v_cvt_pk_bf16_f32 v159, v250, v251
	s_nop 1
	v_permlane16_swap_b32_e32 v156, v158
	v_permlane16_swap_b32_e32 v157, v159
	s_add_u32 s28, s22, 0x400
	s_addc_u32 s29, s23, 0
	global_store_dwordx4 v254, v[156:159], s[28:29]
	v_add_f32_e32 v178, v64, v178
	v_add_f32_e32 v179, v65, v179
	v_add_f32_e32 v180, v66, v180
	v_add_f32_e32 v181, v67, v181
	global_store_dwordx4 v244, v[178:181], s[26:27] offset:128
	v_mul_f32_e32 v158, v178, v178
	v_mul_f32_e32 v159, v179, v179
	v_mul_f32_e32 v250, v180, v180
	v_mul_f32_e32 v251, v181, v181
	v_add_f32_e32 v158, v158, v159
	v_add_f32_e32 v250, v250, v251
	v_add_f32_e32 v158, v158, v250
	v_add_f32_e32 v161, v161, v158
	v_mul_f32_e32 v156, v178, v216
	v_mul_f32_e32 v157, v179, v217
	v_mul_f32_e32 v158, v180, v218
	v_mul_f32_e32 v159, v181, v219
	v_cvt_pk_bf16_f32 v156, v156, v157
	v_cvt_pk_bf16_f32 v157, v158, v159
	v_add_f32_e32 v182, v60, v182
	v_add_f32_e32 v183, v61, v183
	v_add_f32_e32 v184, v62, v184
	v_add_f32_e32 v185, v63, v185
	global_store_dwordx4 v244, v[182:185], s[26:27] offset:192
	v_mul_f32_e32 v158, v182, v182
	v_mul_f32_e32 v159, v183, v183
	v_mul_f32_e32 v250, v184, v184
	v_mul_f32_e32 v251, v185, v185
	v_add_f32_e32 v158, v158, v159
	v_add_f32_e32 v250, v250, v251
	v_add_f32_e32 v158, v158, v250
	v_add_f32_e32 v161, v161, v158
	v_mul_f32_e32 v158, v182, v220
	v_mul_f32_e32 v159, v183, v221
	v_mul_f32_e32 v250, v184, v222
	v_mul_f32_e32 v251, v185, v223
	v_cvt_pk_bf16_f32 v158, v158, v159
	v_cvt_pk_bf16_f32 v159, v250, v251
	s_nop 1
	v_permlane16_swap_b32_e32 v156, v158
	v_permlane16_swap_b32_e32 v157, v159
	s_add_u32 s28, s22, 0x200400
	s_addc_u32 s29, s23, 0
	global_store_dwordx4 v254, v[156:159], s[28:29]
	ds_bpermute_b32 v158, v248, v161
	s_waitcnt lgkmcnt(0)
	v_add_f32_e32 v161, v161, v158
	ds_bpermute_b32 v158, v249, v161
	s_waitcnt lgkmcnt(0)
	v_add_f32_e32 v161, v161, v158
	global_store_dword v247, v161, s[30:31]
	global_load_dwordx4 v[170:173], v244, s[24:25]
	global_load_dwordx4 v[174:177], v244, s[24:25] offset:64
	global_load_dwordx4 v[178:181], v244, s[24:25] offset:128
	global_load_dwordx4 v[182:185], v244, s[24:25] offset:192
	s_waitcnt vmcnt(33)
	v_add_f32_e32 v186, v36, v186
	v_add_f32_e32 v187, v37, v187
	v_add_f32_e32 v188, v38, v188
	v_add_f32_e32 v189, v39, v189
	global_store_dwordx4 v244, v[186:189], s[26:27] offset:256
	v_mul_f32_e32 v158, v186, v186
	v_mul_f32_e32 v159, v187, v187
	v_mul_f32_e32 v250, v188, v188
	v_mul_f32_e32 v251, v189, v189
	v_add_f32_e32 v158, v158, v159
	v_add_f32_e32 v250, v250, v251
	v_add_f32_e32 v161, v158, v250
	v_mul_f32_e32 v156, v186, v224
	v_mul_f32_e32 v157, v187, v225
	v_mul_f32_e32 v158, v188, v226
	v_mul_f32_e32 v159, v189, v227
	v_cvt_pk_bf16_f32 v156, v156, v157
	v_cvt_pk_bf16_f32 v157, v158, v159
	v_add_f32_e32 v190, v32, v190
	v_add_f32_e32 v191, v33, v191
	v_add_f32_e32 v192, v34, v192
	v_add_f32_e32 v193, v35, v193
	global_store_dwordx4 v244, v[190:193], s[26:27] offset:320
	v_mul_f32_e32 v158, v190, v190
	v_mul_f32_e32 v159, v191, v191
	v_mul_f32_e32 v250, v192, v192
	v_mul_f32_e32 v251, v193, v193
	v_add_f32_e32 v158, v158, v159
	v_add_f32_e32 v250, v250, v251
	v_add_f32_e32 v158, v158, v250
	v_add_f32_e32 v161, v161, v158
	v_mul_f32_e32 v158, v190, v228
	v_mul_f32_e32 v159, v191, v229
	v_mul_f32_e32 v250, v192, v230
	v_mul_f32_e32 v251, v193, v231
	v_cvt_pk_bf16_f32 v158, v158, v159
	v_cvt_pk_bf16_f32 v159, v250, v251
	s_nop 1
	v_permlane16_swap_b32_e32 v156, v158
	v_permlane16_swap_b32_e32 v157, v159
	s_add_u32 s28, s22, 0x400400
	s_addc_u32 s29, s23, 0
	global_store_dwordx4 v254, v[156:159], s[28:29]
	v_add_f32_e32 v194, v28, v194
	v_add_f32_e32 v195, v29, v195
	v_add_f32_e32 v196, v30, v196
	v_add_f32_e32 v197, v31, v197
	global_store_dwordx4 v244, v[194:197], s[26:27] offset:384
	v_mul_f32_e32 v158, v194, v194
	v_mul_f32_e32 v159, v195, v195
	v_mul_f32_e32 v250, v196, v196
	v_mul_f32_e32 v251, v197, v197
	v_add_f32_e32 v158, v158, v159
	v_add_f32_e32 v250, v250, v251
	v_add_f32_e32 v158, v158, v250
	v_add_f32_e32 v161, v161, v158
	v_mul_f32_e32 v156, v194, v232
	v_mul_f32_e32 v157, v195, v233
	v_mul_f32_e32 v158, v196, v234
	v_mul_f32_e32 v159, v197, v235
	v_cvt_pk_bf16_f32 v156, v156, v157
	v_cvt_pk_bf16_f32 v157, v158, v159
	v_add_f32_e32 v240, v24, v240
	v_add_f32_e32 v241, v25, v241
	v_add_f32_e32 v242, v26, v242
	v_add_f32_e32 v243, v27, v243
	global_store_dwordx4 v244, v[240:243], s[26:27] offset:448
	v_mul_f32_e32 v158, v240, v240
	v_mul_f32_e32 v159, v241, v241
	v_mul_f32_e32 v250, v242, v242
	v_mul_f32_e32 v251, v243, v243
	v_add_f32_e32 v158, v158, v159
	v_add_f32_e32 v250, v250, v251
	v_add_f32_e32 v158, v158, v250
	v_add_f32_e32 v161, v161, v158
	v_mul_f32_e32 v158, v240, v236
	v_mul_f32_e32 v159, v241, v237
	v_mul_f32_e32 v250, v242, v238
	v_mul_f32_e32 v251, v243, v239
	v_cvt_pk_bf16_f32 v158, v158, v159
	v_cvt_pk_bf16_f32 v159, v250, v251
	s_nop 1
	v_permlane16_swap_b32_e32 v156, v158
	v_permlane16_swap_b32_e32 v157, v159
	s_add_u32 s28, s22, 0x600400
	s_addc_u32 s29, s23, 0
	global_store_dwordx4 v254, v[156:159], s[28:29]
	ds_bpermute_b32 v158, v248, v161
	s_waitcnt lgkmcnt(0)
	v_add_f32_e32 v161, v161, v158
	ds_bpermute_b32 v158, v249, v161
	s_waitcnt lgkmcnt(0)
	v_add_f32_e32 v161, v161, v158
	global_store_dword v247, v161, s[30:31] offset:4
	s_add_u32 s26, s26, 0x10000
	s_addc_u32 s27, s27, 0
	s_add_u32 s30, s30, 0x400
	s_addc_u32 s31, s31, 0
	global_load_dwordx4 v[186:189], v244, s[24:25] offset:256
	global_load_dwordx4 v[190:193], v244, s[24:25] offset:320
	global_load_dwordx4 v[194:197], v244, s[24:25] offset:384
	global_load_dwordx4 v[240:243], v244, s[24:25] offset:448
	s_add_u32 s24, s24, 0x10000
	s_addc_u32 s25, s25, 0
	s_waitcnt vmcnt(33)
	v_add_f32_e32 v0, v108, v0
	v_add_f32_e32 v1, v109, v1
	v_add_f32_e32 v2, v110, v2
	v_add_f32_e32 v3, v111, v3
	global_store_dwordx4 v244, v[0:3], s[26:27]
	v_mul_f32_e32 v158, v0, v0
	v_mul_f32_e32 v159, v1, v1
	v_mul_f32_e32 v250, v2, v2
	v_mul_f32_e32 v251, v3, v3
	v_add_f32_e32 v158, v158, v159
	v_add_f32_e32 v250, v250, v251
	v_add_f32_e32 v161, v158, v250
	v_mul_f32_e32 v156, v0, v208
	v_mul_f32_e32 v157, v1, v209
	v_mul_f32_e32 v158, v2, v210
	v_mul_f32_e32 v159, v3, v211
	v_cvt_pk_bf16_f32 v156, v156, v157
	v_cvt_pk_bf16_f32 v157, v158, v159
	v_add_f32_e32 v4, v112, v4
	v_add_f32_e32 v5, v113, v5
	v_add_f32_e32 v6, v114, v6
	v_add_f32_e32 v7, v115, v7
	global_store_dwordx4 v244, v[4:7], s[26:27] offset:64
	v_mul_f32_e32 v158, v4, v4
	v_mul_f32_e32 v159, v5, v5
	v_mul_f32_e32 v250, v6, v6
	v_mul_f32_e32 v251, v7, v7
	v_add_f32_e32 v158, v158, v159
	v_add_f32_e32 v250, v250, v251
	v_add_f32_e32 v158, v158, v250
	v_add_f32_e32 v161, v161, v158
	v_mul_f32_e32 v158, v4, v212
	v_mul_f32_e32 v159, v5, v213
	v_mul_f32_e32 v250, v6, v214
	v_mul_f32_e32 v251, v7, v215
	v_cvt_pk_bf16_f32 v158, v158, v159
	v_cvt_pk_bf16_f32 v159, v250, v251
	s_nop 1
	v_permlane16_swap_b32_e32 v156, v158
	v_permlane16_swap_b32_e32 v157, v159
	s_add_u32 s28, s22, 0x800
	s_addc_u32 s29, s23, 0
	global_store_dwordx4 v254, v[156:159], s[28:29]
	v_add_f32_e32 v8, v116, v8
	v_add_f32_e32 v9, v117, v9
	v_add_f32_e32 v10, v118, v10
	v_add_f32_e32 v11, v119, v11
	global_store_dwordx4 v244, v[8:11], s[26:27] offset:128
	v_mul_f32_e32 v158, v8, v8
	v_mul_f32_e32 v159, v9, v9
	v_mul_f32_e32 v250, v10, v10
	v_mul_f32_e32 v251, v11, v11
	v_add_f32_e32 v158, v158, v159
	v_add_f32_e32 v250, v250, v251
	v_add_f32_e32 v158, v158, v250
	v_add_f32_e32 v161, v161, v158
	v_mul_f32_e32 v156, v8, v216
	v_mul_f32_e32 v157, v9, v217
	v_mul_f32_e32 v158, v10, v218
	v_mul_f32_e32 v159, v11, v219
	v_cvt_pk_bf16_f32 v156, v156, v157
	v_cvt_pk_bf16_f32 v157, v158, v159
	v_add_f32_e32 v12, v124, v12
	v_add_f32_e32 v13, v125, v13
	v_add_f32_e32 v14, v126, v14
	v_add_f32_e32 v15, v127, v15
	global_store_dwordx4 v244, v[12:15], s[26:27] offset:192
	v_mul_f32_e32 v158, v12, v12
	v_mul_f32_e32 v159, v13, v13
	v_mul_f32_e32 v250, v14, v14
	v_mul_f32_e32 v251, v15, v15
	v_add_f32_e32 v158, v158, v159
	v_add_f32_e32 v250, v250, v251
	v_add_f32_e32 v158, v158, v250
	v_add_f32_e32 v161, v161, v158
	v_mul_f32_e32 v158, v12, v220
	v_mul_f32_e32 v159, v13, v221
	v_mul_f32_e32 v250, v14, v222
	v_mul_f32_e32 v251, v15, v223
	v_cvt_pk_bf16_f32 v158, v158, v159
	v_cvt_pk_bf16_f32 v159, v250, v251
	s_nop 1
	v_permlane16_swap_b32_e32 v156, v158
	v_permlane16_swap_b32_e32 v157, v159
	s_add_u32 s28, s22, 0x200800
	s_addc_u32 s29, s23, 0
	global_store_dwordx4 v254, v[156:159], s[28:29]
	ds_bpermute_b32 v158, v248, v161
	s_waitcnt lgkmcnt(0)
	v_add_f32_e32 v161, v161, v158
	ds_bpermute_b32 v158, v249, v161
	s_waitcnt lgkmcnt(0)
	v_add_f32_e32 v161, v161, v158
	global_store_dword v247, v161, s[30:31]
	s_waitcnt vmcnt(29)
	v_add_f32_e32 v16, v88, v16
	v_add_f32_e32 v17, v89, v17
	v_add_f32_e32 v18, v90, v18
	v_add_f32_e32 v19, v91, v19
	global_store_dwordx4 v244, v[16:19], s[26:27] offset:256
	v_mul_f32_e32 v158, v16, v16
	v_mul_f32_e32 v159, v17, v17
	v_mul_f32_e32 v250, v18, v18
	v_mul_f32_e32 v251, v19, v19
	v_add_f32_e32 v158, v158, v159
	v_add_f32_e32 v250, v250, v251
	v_add_f32_e32 v161, v158, v250
	v_mul_f32_e32 v156, v16, v224
	v_mul_f32_e32 v157, v17, v225
	v_mul_f32_e32 v158, v18, v226
	v_mul_f32_e32 v159, v19, v227
	v_cvt_pk_bf16_f32 v156, v156, v157
	v_cvt_pk_bf16_f32 v157, v158, v159
	v_add_f32_e32 v20, v92, v20
	v_add_f32_e32 v21, v93, v21
	v_add_f32_e32 v22, v94, v22
	v_add_f32_e32 v23, v95, v23
	global_store_dwordx4 v244, v[20:23], s[26:27] offset:320
	v_mul_f32_e32 v158, v20, v20
	v_mul_f32_e32 v159, v21, v21
	v_mul_f32_e32 v250, v22, v22
	v_mul_f32_e32 v251, v23, v23
	v_add_f32_e32 v158, v158, v159
	v_add_f32_e32 v250, v250, v251
	v_add_f32_e32 v158, v158, v250
	v_add_f32_e32 v161, v161, v158
	v_mul_f32_e32 v158, v20, v228
	v_mul_f32_e32 v159, v21, v229
	v_mul_f32_e32 v250, v22, v230
	v_mul_f32_e32 v251, v23, v231
	v_cvt_pk_bf16_f32 v158, v158, v159
	v_cvt_pk_bf16_f32 v159, v250, v251
	s_nop 1
	v_permlane16_swap_b32_e32 v156, v158
	v_permlane16_swap_b32_e32 v157, v159
	s_add_u32 s28, s22, 0x400800
	s_addc_u32 s29, s23, 0
	global_store_dwordx4 v254, v[156:159], s[28:29]
	v_add_f32_e32 v162, v96, v162
	v_add_f32_e32 v163, v97, v163
	v_add_f32_e32 v164, v98, v164
	v_add_f32_e32 v165, v99, v165
	global_store_dwordx4 v244, v[162:165], s[26:27] offset:384
	v_mul_f32_e32 v158, v162, v162
	v_mul_f32_e32 v159, v163, v163
	v_mul_f32_e32 v250, v164, v164
	v_mul_f32_e32 v251, v165, v165
	v_add_f32_e32 v158, v158, v159
	v_add_f32_e32 v250, v250, v251
	v_add_f32_e32 v158, v158, v250
	v_add_f32_e32 v161, v161, v158
	v_mul_f32_e32 v156, v162, v232
	v_mul_f32_e32 v157, v163, v233
	v_mul_f32_e32 v158, v164, v234
	v_mul_f32_e32 v159, v165, v235
	v_cvt_pk_bf16_f32 v156, v156, v157
	v_cvt_pk_bf16_f32 v157, v158, v159
	v_add_f32_e32 v166, v84, v166
	v_add_f32_e32 v167, v85, v167
	v_add_f32_e32 v168, v86, v168
	v_add_f32_e32 v169, v87, v169
	global_store_dwordx4 v244, v[166:169], s[26:27] offset:448
	v_mul_f32_e32 v158, v166, v166
	v_mul_f32_e32 v159, v167, v167
	v_mul_f32_e32 v250, v168, v168
	v_mul_f32_e32 v251, v169, v169
	v_add_f32_e32 v158, v158, v159
	v_add_f32_e32 v250, v250, v251
	v_add_f32_e32 v158, v158, v250
	v_add_f32_e32 v161, v161, v158
	v_mul_f32_e32 v158, v166, v236
	v_mul_f32_e32 v159, v167, v237
	v_mul_f32_e32 v250, v168, v238
	v_mul_f32_e32 v251, v169, v239
	v_cvt_pk_bf16_f32 v158, v158, v159
	v_cvt_pk_bf16_f32 v159, v250, v251
	s_nop 1
	v_permlane16_swap_b32_e32 v156, v158
	v_permlane16_swap_b32_e32 v157, v159
	s_add_u32 s28, s22, 0x600800
	s_addc_u32 s29, s23, 0
	global_store_dwordx4 v254, v[156:159], s[28:29]
	ds_bpermute_b32 v158, v248, v161
	s_waitcnt lgkmcnt(0)
	v_add_f32_e32 v161, v161, v158
	ds_bpermute_b32 v158, v249, v161
	s_waitcnt lgkmcnt(0)
	v_add_f32_e32 v161, v161, v158
	global_store_dword v247, v161, s[30:31] offset:4
	s_add_u32 s26, s26, 0x10000
	s_addc_u32 s27, s27, 0
	s_add_u32 s30, s30, 0x400
	s_addc_u32 s31, s31, 0
	s_waitcnt vmcnt(25)
	v_add_f32_e32 v170, v132, v170
	v_add_f32_e32 v171, v133, v171
	v_add_f32_e32 v172, v134, v172
	v_add_f32_e32 v173, v135, v173
	global_store_dwordx4 v244, v[170:173], s[26:27]
	v_mul_f32_e32 v158, v170, v170
	v_mul_f32_e32 v159, v171, v171
	v_mul_f32_e32 v250, v172, v172
	v_mul_f32_e32 v251, v173, v173
	v_add_f32_e32 v158, v158, v159
	v_add_f32_e32 v250, v250, v251
	v_add_f32_e32 v161, v158, v250
	v_mul_f32_e32 v156, v170, v208
	v_mul_f32_e32 v157, v171, v209
	v_mul_f32_e32 v158, v172, v210
	v_mul_f32_e32 v159, v173, v211
	v_cvt_pk_bf16_f32 v156, v156, v157
	v_cvt_pk_bf16_f32 v157, v158, v159
	v_add_f32_e32 v174, v136, v174
	v_add_f32_e32 v175, v137, v175
	v_add_f32_e32 v176, v138, v176
	v_add_f32_e32 v177, v139, v177
	global_store_dwordx4 v244, v[174:177], s[26:27] offset:64
	v_mul_f32_e32 v158, v174, v174
	v_mul_f32_e32 v159, v175, v175
	v_mul_f32_e32 v250, v176, v176
	v_mul_f32_e32 v251, v177, v177
	v_add_f32_e32 v158, v158, v159
	v_add_f32_e32 v250, v250, v251
	v_add_f32_e32 v158, v158, v250
	v_add_f32_e32 v161, v161, v158
	v_mul_f32_e32 v158, v174, v212
	v_mul_f32_e32 v159, v175, v213
	v_mul_f32_e32 v250, v176, v214
	v_mul_f32_e32 v251, v177, v215
	v_cvt_pk_bf16_f32 v158, v158, v159
	v_cvt_pk_bf16_f32 v159, v250, v251
	s_nop 1
	v_permlane16_swap_b32_e32 v156, v158
	v_permlane16_swap_b32_e32 v157, v159
	s_add_u32 s28, s22, 0xc00
	s_addc_u32 s29, s23, 0
	global_store_dwordx4 v254, v[156:159], s[28:29]
	v_add_f32_e32 v178, v140, v178
	v_add_f32_e32 v179, v141, v179
	v_add_f32_e32 v180, v142, v180
	v_add_f32_e32 v181, v143, v181
	global_store_dwordx4 v244, v[178:181], s[26:27] offset:128
	v_mul_f32_e32 v158, v178, v178
	v_mul_f32_e32 v159, v179, v179
	v_mul_f32_e32 v250, v180, v180
	v_mul_f32_e32 v251, v181, v181
	v_add_f32_e32 v158, v158, v159
	v_add_f32_e32 v250, v250, v251
	v_add_f32_e32 v158, v158, v250
	v_add_f32_e32 v161, v161, v158
	v_mul_f32_e32 v156, v178, v216
	v_mul_f32_e32 v157, v179, v217
	v_mul_f32_e32 v158, v180, v218
	v_mul_f32_e32 v159, v181, v219
	v_cvt_pk_bf16_f32 v156, v156, v157
	v_cvt_pk_bf16_f32 v157, v158, v159
	v_add_f32_e32 v182, v144, v182
	v_add_f32_e32 v183, v145, v183
	v_add_f32_e32 v184, v146, v184
	v_add_f32_e32 v185, v147, v185
	global_store_dwordx4 v244, v[182:185], s[26:27] offset:192
	v_mul_f32_e32 v158, v182, v182
	v_mul_f32_e32 v159, v183, v183
	v_mul_f32_e32 v250, v184, v184
	v_mul_f32_e32 v251, v185, v185
	v_add_f32_e32 v158, v158, v159
	v_add_f32_e32 v250, v250, v251
	v_add_f32_e32 v158, v158, v250
	v_add_f32_e32 v161, v161, v158
	v_mul_f32_e32 v158, v182, v220
	v_mul_f32_e32 v159, v183, v221
	v_mul_f32_e32 v250, v184, v222
	v_mul_f32_e32 v251, v185, v223
	v_cvt_pk_bf16_f32 v158, v158, v159
	v_cvt_pk_bf16_f32 v159, v250, v251
	s_nop 1
	v_permlane16_swap_b32_e32 v156, v158
	v_permlane16_swap_b32_e32 v157, v159
	s_add_u32 s28, s22, 0x200c00
	s_addc_u32 s29, s23, 0
	global_store_dwordx4 v254, v[156:159], s[28:29]
	ds_bpermute_b32 v158, v248, v161
	s_waitcnt lgkmcnt(0)
	v_add_f32_e32 v161, v161, v158
	ds_bpermute_b32 v158, v249, v161
	s_waitcnt lgkmcnt(0)
	v_add_f32_e32 v161, v161, v158
	global_store_dword v247, v161, s[30:31]
	s_waitcnt vmcnt(21)
	v_add_f32_e32 v186, v76, v186
	v_add_f32_e32 v187, v77, v187
	v_add_f32_e32 v188, v78, v188
	v_add_f32_e32 v189, v79, v189
	global_store_dwordx4 v244, v[186:189], s[26:27] offset:256
	v_mul_f32_e32 v158, v186, v186
	v_mul_f32_e32 v159, v187, v187
	v_mul_f32_e32 v250, v188, v188
	v_mul_f32_e32 v251, v189, v189
	v_add_f32_e32 v158, v158, v159
	v_add_f32_e32 v250, v250, v251
	v_add_f32_e32 v161, v158, v250
	v_mul_f32_e32 v156, v186, v224
	v_mul_f32_e32 v157, v187, v225
	v_mul_f32_e32 v158, v188, v226
	v_mul_f32_e32 v159, v189, v227
	v_cvt_pk_bf16_f32 v156, v156, v157
	v_cvt_pk_bf16_f32 v157, v158, v159
	v_add_f32_e32 v190, v52, v190
	v_add_f32_e32 v191, v53, v191
	v_add_f32_e32 v192, v54, v192
	v_add_f32_e32 v193, v55, v193
	global_store_dwordx4 v244, v[190:193], s[26:27] offset:320
	v_mul_f32_e32 v158, v190, v190
	v_mul_f32_e32 v159, v191, v191
	v_mul_f32_e32 v250, v192, v192
	v_mul_f32_e32 v251, v193, v193
	v_add_f32_e32 v158, v158, v159
	v_add_f32_e32 v250, v250, v251
	v_add_f32_e32 v158, v158, v250
	v_add_f32_e32 v161, v161, v158
	v_mul_f32_e32 v158, v190, v228
	v_mul_f32_e32 v159, v191, v229
	v_mul_f32_e32 v250, v192, v230
	v_mul_f32_e32 v251, v193, v231
	v_cvt_pk_bf16_f32 v158, v158, v159
	v_cvt_pk_bf16_f32 v159, v250, v251
	s_nop 1
	v_permlane16_swap_b32_e32 v156, v158
	v_permlane16_swap_b32_e32 v157, v159
	s_add_u32 s28, s22, 0x400c00
	s_addc_u32 s29, s23, 0
	global_store_dwordx4 v254, v[156:159], s[28:29]
	v_add_f32_e32 v194, v44, v194
	v_add_f32_e32 v195, v45, v195
	v_add_f32_e32 v196, v46, v196
	v_add_f32_e32 v197, v47, v197
	global_store_dwordx4 v244, v[194:197], s[26:27] offset:384
	v_mul_f32_e32 v158, v194, v194
	v_mul_f32_e32 v159, v195, v195
	v_mul_f32_e32 v250, v196, v196
	v_mul_f32_e32 v251, v197, v197
	v_add_f32_e32 v158, v158, v159
	v_add_f32_e32 v250, v250, v251
	v_add_f32_e32 v158, v158, v250
	v_add_f32_e32 v161, v161, v158
	v_mul_f32_e32 v156, v194, v232
	v_mul_f32_e32 v157, v195, v233
	v_mul_f32_e32 v158, v196, v234
	v_mul_f32_e32 v159, v197, v235
	v_cvt_pk_bf16_f32 v156, v156, v157
	v_cvt_pk_bf16_f32 v157, v158, v159
	v_add_f32_e32 v240, v148, v240
	v_add_f32_e32 v241, v149, v241
	v_add_f32_e32 v242, v150, v242
	v_add_f32_e32 v243, v151, v243
	global_store_dwordx4 v244, v[240:243], s[26:27] offset:448
	v_mul_f32_e32 v158, v240, v240
	v_mul_f32_e32 v159, v241, v241
	v_mul_f32_e32 v250, v242, v242
	v_mul_f32_e32 v251, v243, v243
	v_add_f32_e32 v158, v158, v159
	v_add_f32_e32 v250, v250, v251
	v_add_f32_e32 v158, v158, v250
	v_add_f32_e32 v161, v161, v158
	v_mul_f32_e32 v158, v240, v236
	v_mul_f32_e32 v159, v241, v237
	v_mul_f32_e32 v250, v242, v238
	v_mul_f32_e32 v251, v243, v239
	v_cvt_pk_bf16_f32 v158, v158, v159
	v_cvt_pk_bf16_f32 v159, v250, v251
	s_nop 1
	v_permlane16_swap_b32_e32 v156, v158
	v_permlane16_swap_b32_e32 v157, v159
	s_add_u32 s28, s22, 0x600c00
	s_addc_u32 s29, s23, 0
	global_store_dwordx4 v254, v[156:159], s[28:29]
	ds_bpermute_b32 v158, v248, v161
	s_waitcnt lgkmcnt(0)
	v_add_f32_e32 v161, v161, v158
	ds_bpermute_b32 v158, v249, v161
	s_waitcnt lgkmcnt(0)
	v_add_f32_e32 v161, v161, v158
	global_store_dword v247, v161, s[30:31] offset:4
	s_add_u32 s26, s26, 0x10000
	s_addc_u32 s27, s27, 0
	s_add_u32 s30, s30, 0x400
	s_addc_u32 s31, s31, 0
	s_branch .LBB0_23
